# GEMM K-loops: barrier closing each MFMA block issued 4 MFMAs before the end of the block (no matrix-pipe drain at the role switch)
# baseline (speedup 1.0000x reference)
; #define PG8_STAGE(bufoff, gbase, voff) do { _Pragma("unroll") for (int _i = 0; _i < 2; ++_i) \
;         __builtin_amdgcn_global_load_lds((const unsigned*)((const char*)(gbase) + (voff)[_i]), (PG8_LAS unsigned*)(lds + (bufoff) + ldsw + _i * 8192), 16, 0, 0); } while (0)
; #define PG8_LDA(dst, b, h) do { _Pragma("unroll") for (int m = 0; m < 4; ++m) _Pragma("unroll") for (int k = 0; k < 2; ++k) dst[m][k] = *(const PG8_LAS bf16x8*)(lds + PG8_SA(b, h) + aoff + m * 2048 + k * 1024); } while (0)
; #define PG8_LDB(dst, b, h) do { _Pragma("unroll") for (int n = 0; n < 2; ++n) _Pragma("unroll") for (int k = 0; k < 2; ++k) dst[n][k] = *(const PG8_LAS bf16x8*)(lds + PG8_SB(b, h) + boff + n * 2048 + k * 1024); } while (0)
; #define PG8_MMA(ai, bj, At, Bt) do { __builtin_amdgcn_s_setprio(1); _Pragma("unroll") for (int m = 0; m < 4; ++m) _Pragma("unroll") for (int n = 0; n < 2; ++n) _Pragma("unroll") for (int k = 0; k < 2; ++k) \
;         acc[ai][bj][m][n] = __builtin_amdgcn_mfma_f32_16x16x32_bf16(Bt[n][k], At[m][k], acc[ai][bj][m][n], 0, 0, 0); __builtin_amdgcn_s_setprio(0); } while (0)
; #define PG8_WAIT_V(n) asm volatile("s_waitcnt vmcnt(" #n ")" ::: "memory")
; #define PG8_WAIT_L(n) asm volatile("s_waitcnt lgkmcnt(" #n ")" ::: "memory")
; #define PG8_BAR __builtin_amdgcn_s_barrier()
; #define PG8_SCHED __builtin_amdgcn_sched_barrier(0)
; template <class Epi, class Sched, bool ALIGN_EPI = false, bool SP2 = false>
; __device__ __forceinline__ void gemm_phase(PG8_LAS unsigned char* lds, const Gemm g, const Sched& S, const Epi& E) {
;     ...
;         for (int t = 0; t < nt; t += 2) {
;             const bool last = (t == nt - 2);
;             const char* a1 = cA + (size_t)(t + 1) * kstep;
;             const char* a2 = last ? nA : cA + (size_t)(t + 2) * kstep; const char* b2 = last ? nB : cB + (size_t)(t + 2) * kstep;
;             const char* a3 = a2 + kstep; const char* b3 = b2 + kstep;
;             if (last && has_next) S.a_ready(nxt);
;             if constexpr (SP2) {
;             PG8_LDB(B0, 0, 0); PG8_LDB(B1, 0, 1); PG8_SCHED; PG8_LDA(At, 0, 0); PG8_STAGE(PG8_SA(1, 1), a1 + hstep, voffA);
;             PG8_WAIT_V(8); PG8_WAIT_L(0); PG8_BAR; PG8_MMA(0, 0, At, B0); PG8_MMA(0, 1, At, B1); PG8_BAR; PG8_SCHED;
;             PG8_LDA(At, 0, 1); PG8_STAGE(PG8_SB(0, 0), b2, voffB); PG8_STAGE(PG8_SB(0, 1), b2 + hstep, voffB); PG8_STAGE(PG8_SA(0, 0), a2, voffA);
.LBB0_132:
	s_add_u32 s18, s46, 0xfffc0080
	s_addc_u32 s38, s47, -1
	s_add_i32 s39, 0, 0x10000
	s_cmp_eq_u32 s85, 12
	s_cselect_b32 s81, s33, s38
	s_cselect_b32 s80, s73, s18
	v_add_u32_e32 v0, s39, v176
	s_cselect_b32 s45, s75, s84
	s_cselect_b32 s44, s82, s83
	s_add_i32 s18, 0, 0x14000
	ds_read_b128 v[144:147], v0
	ds_read_b128 v[148:151], v0 offset:1024
	ds_read_b128 v[152:155], v0 offset:2048
	ds_read_b128 v[156:159], v0 offset:3072
	v_add_u32_e32 v0, s18, v176
	ds_read_b128 v[160:163], v0
	ds_read_b128 v[164:167], v0 offset:1024
	ds_read_b128 v[168:171], v0 offset:2048
	ds_read_b128 v[172:175], v0 offset:3072
	v_lshl_add_u64 v[218:219], s[46:47], 0, v[140:141]
	s_add_i32 m0, s92, 0xc000
	ds_read_b128 v[180:183], v178
	ds_read_b128 v[184:187], v178 offset:1024
	ds_read_b128 v[188:191], v178 offset:2048
	ds_read_b128 v[192:195], v178 offset:3072
	ds_read_b128 v[202:205], v178 offset:4096
	ds_read_b128 v[206:209], v178 offset:5120
	ds_read_b128 v[210:213], v178 offset:6144
	ds_read_b128 v[214:217], v178 offset:7168
	global_load_lds_dwordx4 v[218:219], off
	v_lshl_add_u64 v[218:219], s[46:47], 0, v[142:143]
	s_add_i32 m0, s92, 0xe000
	s_nop 0
	global_load_lds_dwordx4 v[218:219], off
	s_waitcnt vmcnt(8)
	s_waitcnt lgkmcnt(0)
	s_barrier
	s_setprio 1
	s_waitcnt lgkmcnt(0)
	v_mfma_f32_16x16x32_bf16 v[118:121], v[144:147], v[180:183], v[118:121]
	v_mfma_f32_16x16x32_bf16 v[114:117], v[152:155], v[180:183], v[114:117]
	v_mfma_f32_16x16x32_bf16 v[102:105], v[144:147], v[188:191], v[102:105]
	v_mfma_f32_16x16x32_bf16 v[98:101], v[152:155], v[188:191], v[98:101]
	v_mfma_f32_16x16x32_bf16 v[86:89], v[144:147], v[202:205], v[86:89]
	v_mfma_f32_16x16x32_bf16 v[82:85], v[152:155], v[202:205], v[82:85]
	v_mfma_f32_16x16x32_bf16 v[70:73], v[144:147], v[210:213], v[70:73]
	v_mfma_f32_16x16x32_bf16 v[66:69], v[152:155], v[210:213], v[66:69]
	v_mfma_f32_16x16x32_bf16 v[118:121], v[148:151], v[184:187], v[118:121]
	v_mfma_f32_16x16x32_bf16 v[114:117], v[156:159], v[184:187], v[114:117]
	v_mfma_f32_16x16x32_bf16 v[102:105], v[148:151], v[192:195], v[102:105]
	v_mfma_f32_16x16x32_bf16 v[98:101], v[156:159], v[192:195], v[98:101]
	v_mfma_f32_16x16x32_bf16 v[86:89], v[148:151], v[206:209], v[86:89]
	v_mfma_f32_16x16x32_bf16 v[82:85], v[156:159], v[206:209], v[82:85]
	v_mfma_f32_16x16x32_bf16 v[70:73], v[148:151], v[214:217], v[70:73]
	v_mfma_f32_16x16x32_bf16 v[66:69], v[156:159], v[214:217], v[66:69]
	s_setprio 0
	s_setprio 1
	v_mfma_f32_16x16x32_bf16 v[126:129], v[160:163], v[180:183], v[126:129]
	v_mfma_f32_16x16x32_bf16 v[122:125], v[168:171], v[180:183], v[122:125]
	v_mfma_f32_16x16x32_bf16 v[110:113], v[160:163], v[188:191], v[110:113]
	v_mfma_f32_16x16x32_bf16 v[106:109], v[168:171], v[188:191], v[106:109]
	v_mfma_f32_16x16x32_bf16 v[94:97], v[160:163], v[202:205], v[94:97]
	v_mfma_f32_16x16x32_bf16 v[90:93], v[168:171], v[202:205], v[90:93]
	v_mfma_f32_16x16x32_bf16 v[78:81], v[160:163], v[210:213], v[78:81]
	v_mfma_f32_16x16x32_bf16 v[74:77], v[168:171], v[210:213], v[74:77]
	v_mfma_f32_16x16x32_bf16 v[126:129], v[164:167], v[184:187], v[126:129]
	v_mfma_f32_16x16x32_bf16 v[122:125], v[172:175], v[184:187], v[122:125]
	v_mfma_f32_16x16x32_bf16 v[110:113], v[164:167], v[192:195], v[110:113]
	v_mfma_f32_16x16x32_bf16 v[106:109], v[172:175], v[192:195], v[106:109]
	s_barrier
	v_mfma_f32_16x16x32_bf16 v[94:97], v[164:167], v[206:209], v[94:97]
	v_mfma_f32_16x16x32_bf16 v[90:93], v[172:175], v[206:209], v[90:93]
	v_mfma_f32_16x16x32_bf16 v[78:81], v[164:167], v[214:217], v[78:81]
	v_mfma_f32_16x16x32_bf16 v[74:77], v[172:175], v[214:217], v[74:77]
	s_setprio 0
	s_add_i32 s38, s39, s91
	v_lshl_add_u64 v[218:219], s[44:45], 0, v[134:135]
	s_mov_b32 m0, s38
	ds_read_b128 v[180:183], v178 offset:16384
	ds_read_b128 v[184:187], v178 offset:17408
	ds_read_b128 v[188:191], v178 offset:18432
	ds_read_b128 v[192:195], v178 offset:19456
	ds_read_b128 v[202:205], v178 offset:20480
	ds_read_b128 v[206:209], v178 offset:21504
	ds_read_b128 v[210:213], v178 offset:22528
	ds_read_b128 v[214:217], v178 offset:23552
	global_load_lds_dwordx4 v[218:219], off
	s_add_i32 m0, s38, 0x2000
	s_add_u32 s38, s44, 0x40000
	v_lshl_add_u64 v[220:221], s[44:45], 0, v[130:131]
	s_addc_u32 s39, s45, 0
	s_add_i32 s18, s18, s91
	global_load_lds_dwordx4 v[220:221], off
	v_lshl_add_u64 v[222:223], s[38:39], 0, v[134:135]
	s_mov_b32 m0, s18
	v_lshl_add_u64 v[224:225], s[80:81], 0, v[132:133]
	global_load_lds_dwordx4 v[222:223], off
	v_lshl_add_u64 v[222:223], s[38:39], 0, v[130:131]
	s_add_i32 m0, s18, 0x2000
	s_nop 0
	global_load_lds_dwordx4 v[222:223], off
	v_lshl_add_u64 v[222:223], s[80:81], 0, v[136:137]
	s_mov_b32 m0, s92
	s_nop 0
	global_load_lds_dwordx4 v[222:223], off
	s_mov_b32 m0, s93
	s_nop 0
	global_load_lds_dwordx4 v[224:225], off
	s_waitcnt vmcnt(8)
	s_waitcnt lgkmcnt(0)
	s_barrier
; #define PG8_STAGE(bufoff, gbase, voff) do { _Pragma("unroll") for (int _i = 0; _i < 2; ++_i) \
;         __builtin_amdgcn_global_load_lds((const unsigned*)((const char*)(gbase) + (voff)[_i]), (PG8_LAS unsigned*)(lds + (bufoff) + ldsw + _i * 8192), 16, 0, 0); } while (0)
; #define PG8_LDA(dst, b, h) do { _Pragma("unroll") for (int m = 0; m < 4; ++m) _Pragma("unroll") for (int k = 0; k < 2; ++k) dst[m][k] = *(const PG8_LAS bf16x8*)(lds + PG8_SA(b, h) + aoff + m * 2048 + k * 1024); } while (0)
; #define PG8_LDB(dst, b, h) do { _Pragma("unroll") for (int n = 0; n < 2; ++n) _Pragma("unroll") for (int k = 0; k < 2; ++k) dst[n][k] = *(const PG8_LAS bf16x8*)(lds + PG8_SB(b, h) + boff + n * 2048 + k * 1024); } while (0)
; #define PG8_MMA(ai, bj, At, Bt) do { __builtin_amdgcn_s_setprio(1); _Pragma("unroll") for (int m = 0; m < 4; ++m) _Pragma("unroll") for (int n = 0; n < 2; ++n) _Pragma("unroll") for (int k = 0; k < 2; ++k) \
;         acc[ai][bj][m][n] = __builtin_amdgcn_mfma_f32_16x16x32_bf16(Bt[n][k], At[m][k], acc[ai][bj][m][n], 0, 0, 0); __builtin_amdgcn_s_setprio(0); } while (0)
; #define PG8_WAIT_V(n) asm volatile("s_waitcnt vmcnt(" #n ")" ::: "memory")
; #define PG8_WAIT_L(n) asm volatile("s_waitcnt lgkmcnt(" #n ")" ::: "memory")
; #define PG8_BAR __builtin_amdgcn_s_barrier()
; #define PG8_SCHED __builtin_amdgcn_sched_barrier(0)
; template <class Epi, class Sched, bool ALIGN_EPI = false, bool SP2 = false>
; __device__ __forceinline__ void gemm_phase(PG8_LAS unsigned char* lds, const Gemm g, const Sched& S, const Epi& E) {
;     ...
;             PG8_WAIT_V(8); PG8_WAIT_L(0); PG8_BAR; PG8_MMA(1, 0, At, B0); PG8_MMA(1, 1, At, B1); PG8_BAR; PG8_SCHED;
;             PG8_LDB(B0, 1, 0); PG8_LDB(B1, 1, 1); PG8_SCHED; PG8_LDA(At, 1, 0); PG8_STAGE(PG8_SA(0, 1), a2 + hstep, voffA);
;             PG8_WAIT_V(8); PG8_WAIT_L(0); PG8_BAR; PG8_MMA(0, 0, At, B0); PG8_MMA(0, 1, At, B1); PG8_BAR; PG8_SCHED;
	s_setprio 1
	s_waitcnt lgkmcnt(0)
	v_mfma_f32_16x16x32_bf16 v[54:57], v[144:147], v[180:183], v[54:57]
	v_mfma_f32_16x16x32_bf16 v[50:53], v[152:155], v[180:183], v[50:53]
	v_mfma_f32_16x16x32_bf16 v[38:41], v[144:147], v[188:191], v[38:41]
	v_mfma_f32_16x16x32_bf16 v[34:37], v[152:155], v[188:191], v[34:37]
	v_mfma_f32_16x16x32_bf16 v[22:25], v[144:147], v[202:205], v[22:25]
	v_mfma_f32_16x16x32_bf16 v[18:21], v[152:155], v[202:205], v[18:21]
	v_mfma_f32_16x16x32_bf16 v[6:9], v[144:147], v[210:213], v[6:9]
	v_mfma_f32_16x16x32_bf16 v[2:5], v[152:155], v[210:213], v[2:5]
	v_mfma_f32_16x16x32_bf16 v[54:57], v[148:151], v[184:187], v[54:57]
	v_mfma_f32_16x16x32_bf16 v[50:53], v[156:159], v[184:187], v[50:53]
	v_mfma_f32_16x16x32_bf16 v[38:41], v[148:151], v[192:195], v[38:41]
	v_mfma_f32_16x16x32_bf16 v[34:37], v[156:159], v[192:195], v[34:37]
	v_mfma_f32_16x16x32_bf16 v[22:25], v[148:151], v[206:209], v[22:25]
	v_mfma_f32_16x16x32_bf16 v[18:21], v[156:159], v[206:209], v[18:21]
	v_mfma_f32_16x16x32_bf16 v[6:9], v[148:151], v[214:217], v[6:9]
	v_mfma_f32_16x16x32_bf16 v[2:5], v[156:159], v[214:217], v[2:5]
	s_setprio 0
	s_setprio 1
	v_mfma_f32_16x16x32_bf16 v[62:65], v[160:163], v[180:183], v[62:65]
	v_mfma_f32_16x16x32_bf16 v[58:61], v[168:171], v[180:183], v[58:61]
	v_mfma_f32_16x16x32_bf16 v[46:49], v[160:163], v[188:191], v[46:49]
	v_mfma_f32_16x16x32_bf16 v[42:45], v[168:171], v[188:191], v[42:45]
	v_mfma_f32_16x16x32_bf16 v[30:33], v[160:163], v[202:205], v[30:33]
	v_mfma_f32_16x16x32_bf16 v[26:29], v[168:171], v[202:205], v[26:29]
	v_mfma_f32_16x16x32_bf16 v[10:13], v[160:163], v[210:213], v[10:13]
	v_mfma_f32_16x16x32_bf16 v[14:17], v[168:171], v[210:213], v[14:17]
	v_mfma_f32_16x16x32_bf16 v[62:65], v[164:167], v[184:187], v[62:65]
	v_mfma_f32_16x16x32_bf16 v[58:61], v[172:175], v[184:187], v[58:61]
	v_mfma_f32_16x16x32_bf16 v[46:49], v[164:167], v[192:195], v[46:49]
	v_mfma_f32_16x16x32_bf16 v[42:45], v[172:175], v[192:195], v[42:45]
	s_barrier
	v_mfma_f32_16x16x32_bf16 v[30:33], v[164:167], v[206:209], v[30:33]
	v_mfma_f32_16x16x32_bf16 v[26:29], v[172:175], v[206:209], v[26:29]
	v_mfma_f32_16x16x32_bf16 v[10:13], v[164:167], v[214:217], v[10:13]
	v_mfma_f32_16x16x32_bf16 v[14:17], v[172:175], v[214:217], v[14:17]
	s_setprio 0
	s_add_i32 s18, 0, 0x18000
	v_add_u32_e32 v0, s18, v176
	s_add_i32 vcc_lo, 0, 0x1c000
	ds_read_b128 v[144:147], v0
	ds_read_b128 v[148:151], v0 offset:1024
	ds_read_b128 v[152:155], v0 offset:2048
	ds_read_b128 v[156:159], v0 offset:3072
	v_add_u32_e32 v0, vcc_lo, v176
	ds_read_b128 v[160:163], v0
	ds_read_b128 v[164:167], v0 offset:1024
	ds_read_b128 v[168:171], v0 offset:2048
	ds_read_b128 v[172:175], v0 offset:3072
	s_add_u32 s38, s80, 0x40000
	s_addc_u32 s39, s81, 0
	s_mov_b32 m0, s94
	v_lshl_add_u64 v[226:227], s[38:39], 0, v[136:137]
	ds_read_b128 v[180:183], v178 offset:32768
	ds_read_b128 v[184:187], v178 offset:33792
	ds_read_b128 v[188:191], v178 offset:34816
	ds_read_b128 v[192:195], v178 offset:35840
	ds_read_b128 v[202:205], v178 offset:36864
	ds_read_b128 v[206:209], v178 offset:37888
	ds_read_b128 v[210:213], v178 offset:38912
	ds_read_b128 v[214:217], v178 offset:39936
	global_load_lds_dwordx4 v[226:227], off
	v_lshl_add_u64 v[226:227], s[38:39], 0, v[132:133]
	s_mov_b32 m0, s95
	s_nop 0
	global_load_lds_dwordx4 v[226:227], off
	s_waitcnt vmcnt(8)
	s_waitcnt lgkmcnt(0)
	s_barrier
	s_setprio 1
	s_waitcnt lgkmcnt(0)
	v_mfma_f32_16x16x32_bf16 v[118:121], v[144:147], v[180:183], v[118:121]
	v_mfma_f32_16x16x32_bf16 v[114:117], v[152:155], v[180:183], v[114:117]
	v_mfma_f32_16x16x32_bf16 v[102:105], v[144:147], v[188:191], v[102:105]
	v_mfma_f32_16x16x32_bf16 v[98:101], v[152:155], v[188:191], v[98:101]
	v_mfma_f32_16x16x32_bf16 v[86:89], v[144:147], v[202:205], v[86:89]
	v_mfma_f32_16x16x32_bf16 v[82:85], v[152:155], v[202:205], v[82:85]
	v_mfma_f32_16x16x32_bf16 v[70:73], v[144:147], v[210:213], v[70:73]
	v_mfma_f32_16x16x32_bf16 v[66:69], v[152:155], v[210:213], v[66:69]
	v_mfma_f32_16x16x32_bf16 v[118:121], v[148:151], v[184:187], v[118:121]
	v_mfma_f32_16x16x32_bf16 v[114:117], v[156:159], v[184:187], v[114:117]
	v_mfma_f32_16x16x32_bf16 v[102:105], v[148:151], v[192:195], v[102:105]
	v_mfma_f32_16x16x32_bf16 v[98:101], v[156:159], v[192:195], v[98:101]
	v_mfma_f32_16x16x32_bf16 v[86:89], v[148:151], v[206:209], v[86:89]
	v_mfma_f32_16x16x32_bf16 v[82:85], v[156:159], v[206:209], v[82:85]
	v_mfma_f32_16x16x32_bf16 v[70:73], v[148:151], v[214:217], v[70:73]
	v_mfma_f32_16x16x32_bf16 v[66:69], v[156:159], v[214:217], v[66:69]
	s_setprio 0
	s_setprio 1
	v_mfma_f32_16x16x32_bf16 v[126:129], v[160:163], v[180:183], v[126:129]
	v_mfma_f32_16x16x32_bf16 v[122:125], v[168:171], v[180:183], v[122:125]
	v_mfma_f32_16x16x32_bf16 v[110:113], v[160:163], v[188:191], v[110:113]
	v_mfma_f32_16x16x32_bf16 v[106:109], v[168:171], v[188:191], v[106:109]
	v_mfma_f32_16x16x32_bf16 v[94:97], v[160:163], v[202:205], v[94:97]
	v_mfma_f32_16x16x32_bf16 v[90:93], v[168:171], v[202:205], v[90:93]
	v_mfma_f32_16x16x32_bf16 v[78:81], v[160:163], v[210:213], v[78:81]
	v_mfma_f32_16x16x32_bf16 v[74:77], v[168:171], v[210:213], v[74:77]
	v_mfma_f32_16x16x32_bf16 v[126:129], v[164:167], v[184:187], v[126:129]
	v_mfma_f32_16x16x32_bf16 v[122:125], v[172:175], v[184:187], v[122:125]
	v_mfma_f32_16x16x32_bf16 v[110:113], v[164:167], v[192:195], v[110:113]
	v_mfma_f32_16x16x32_bf16 v[106:109], v[172:175], v[192:195], v[106:109]
	s_barrier
; #define PG8_STAGE(bufoff, gbase, voff) do { _Pragma("unroll") for (int _i = 0; _i < 2; ++_i) \
;         __builtin_amdgcn_global_load_lds((const unsigned*)((const char*)(gbase) + (voff)[_i]), (PG8_LAS unsigned*)(lds + (bufoff) + ldsw + _i * 8192), 16, 0, 0); } while (0)
; #define PG8_LDA(dst, b, h) do { _Pragma("unroll") for (int m = 0; m < 4; ++m) _Pragma("unroll") for (int k = 0; k < 2; ++k) dst[m][k] = *(const PG8_LAS bf16x8*)(lds + PG8_SA(b, h) + aoff + m * 2048 + k * 1024); } while (0)
; #define PG8_MMA(ai, bj, At, Bt) do { __builtin_amdgcn_s_setprio(1); _Pragma("unroll") for (int m = 0; m < 4; ++m) _Pragma("unroll") for (int n = 0; n < 2; ++n) _Pragma("unroll") for (int k = 0; k < 2; ++k) \
;         acc[ai][bj][m][n] = __builtin_amdgcn_mfma_f32_16x16x32_bf16(Bt[n][k], At[m][k], acc[ai][bj][m][n], 0, 0, 0); __builtin_amdgcn_s_setprio(0); } while (0)
; #define PG8_WAIT_V(n) asm volatile("s_waitcnt vmcnt(" #n ")" ::: "memory")
; #define PG8_WAIT_L(n) asm volatile("s_waitcnt lgkmcnt(" #n ")" ::: "memory")
; #define PG8_BAR __builtin_amdgcn_s_barrier()
; #define PG8_SCHED __builtin_amdgcn_sched_barrier(0)
; template <class Epi, class Sched, bool ALIGN_EPI = false, bool SP2 = false>
; __device__ __forceinline__ void gemm_phase(PG8_LAS unsigned char* lds, const Gemm g, const Sched& S, const Epi& E) {
;     ...
;             PG8_WAIT_V(8); PG8_WAIT_L(0); PG8_BAR; PG8_MMA(0, 0, At, B0); PG8_MMA(0, 1, At, B1); PG8_BAR; PG8_SCHED;
;             PG8_LDA(At, 1, 1); PG8_STAGE(PG8_SB(1, 0), b3, voffB); PG8_STAGE(PG8_SB(1, 1), b3 + hstep, voffB); PG8_STAGE(PG8_SA(1, 0), a3, voffA);
;             PG8_WAIT_V(8); PG8_WAIT_L(0); PG8_BAR; PG8_MMA(1, 0, At, B0); PG8_MMA(1, 1, At, B1); PG8_BAR; PG8_SCHED;
	v_mfma_f32_16x16x32_bf16 v[94:97], v[164:167], v[206:209], v[94:97]
	v_mfma_f32_16x16x32_bf16 v[90:93], v[172:175], v[206:209], v[90:93]
	v_mfma_f32_16x16x32_bf16 v[78:81], v[164:167], v[214:217], v[78:81]
	v_mfma_f32_16x16x32_bf16 v[74:77], v[172:175], v[214:217], v[74:77]
	s_setprio 0
	s_add_i32 s18, s18, s91
	v_lshl_add_u64 v[218:219], v[218:219], 0, s[30:31]
	s_mov_b32 m0, s18
	ds_read_b128 v[180:183], v178 offset:49152
	ds_read_b128 v[184:187], v178 offset:50176
	ds_read_b128 v[188:191], v178 offset:51200
	ds_read_b128 v[192:195], v178 offset:52224
	ds_read_b128 v[202:205], v178 offset:53248
	ds_read_b128 v[206:209], v178 offset:54272
	ds_read_b128 v[210:213], v178 offset:55296
	ds_read_b128 v[214:217], v178 offset:56320
	global_load_lds_dwordx4 v[218:219], off
	s_add_i32 m0, s18, 0x2000
	s_add_u32 s38, s44, 0x40080
	v_lshl_add_u64 v[218:219], v[220:221], 0, s[30:31]
	s_addc_u32 s39, s45, 0
	s_add_i32 s18, vcc_lo, s91
	global_load_lds_dwordx4 v[218:219], off
	v_lshl_add_u64 v[218:219], s[38:39], 0, v[134:135]
	s_mov_b32 m0, s18
	s_nop 0
	global_load_lds_dwordx4 v[218:219], off
	v_lshl_add_u64 v[218:219], s[38:39], 0, v[130:131]
	s_add_i32 m0, s18, 0x2000
	s_nop 0
	global_load_lds_dwordx4 v[218:219], off
	v_lshl_add_u64 v[218:219], v[222:223], 0, s[30:31]
	s_mov_b32 m0, s7
	s_nop 0
	global_load_lds_dwordx4 v[218:219], off
	v_lshl_add_u64 v[218:219], v[224:225], 0, s[30:31]
	s_mov_b32 m0, s96
	s_nop 0
	global_load_lds_dwordx4 v[218:219], off
	s_waitcnt vmcnt(8)
	s_waitcnt lgkmcnt(0)
	s_barrier
	s_setprio 1
	s_waitcnt lgkmcnt(0)
	v_mfma_f32_16x16x32_bf16 v[54:57], v[144:147], v[180:183], v[54:57]
	v_mfma_f32_16x16x32_bf16 v[50:53], v[152:155], v[180:183], v[50:53]
	v_mfma_f32_16x16x32_bf16 v[38:41], v[144:147], v[188:191], v[38:41]
	v_mfma_f32_16x16x32_bf16 v[34:37], v[152:155], v[188:191], v[34:37]
	v_mfma_f32_16x16x32_bf16 v[22:25], v[144:147], v[202:205], v[22:25]
	v_mfma_f32_16x16x32_bf16 v[18:21], v[152:155], v[202:205], v[18:21]
	v_mfma_f32_16x16x32_bf16 v[6:9], v[144:147], v[210:213], v[6:9]
	v_mfma_f32_16x16x32_bf16 v[2:5], v[152:155], v[210:213], v[2:5]
	v_mfma_f32_16x16x32_bf16 v[54:57], v[148:151], v[184:187], v[54:57]
	v_mfma_f32_16x16x32_bf16 v[50:53], v[156:159], v[184:187], v[50:53]
	v_mfma_f32_16x16x32_bf16 v[38:41], v[148:151], v[192:195], v[38:41]
	v_mfma_f32_16x16x32_bf16 v[34:37], v[156:159], v[192:195], v[34:37]
	v_mfma_f32_16x16x32_bf16 v[22:25], v[148:151], v[206:209], v[22:25]
	v_mfma_f32_16x16x32_bf16 v[18:21], v[156:159], v[206:209], v[18:21]
	v_mfma_f32_16x16x32_bf16 v[6:9], v[148:151], v[214:217], v[6:9]
	v_mfma_f32_16x16x32_bf16 v[2:5], v[156:159], v[214:217], v[2:5]
	s_setprio 0
	s_setprio 1
	v_mfma_f32_16x16x32_bf16 v[62:65], v[160:163], v[180:183], v[62:65]
	v_mfma_f32_16x16x32_bf16 v[58:61], v[168:171], v[180:183], v[58:61]
	v_mfma_f32_16x16x32_bf16 v[46:49], v[160:163], v[188:191], v[46:49]
	v_mfma_f32_16x16x32_bf16 v[42:45], v[168:171], v[188:191], v[42:45]
	v_mfma_f32_16x16x32_bf16 v[30:33], v[160:163], v[202:205], v[30:33]
	v_mfma_f32_16x16x32_bf16 v[26:29], v[168:171], v[202:205], v[26:29]
	v_mfma_f32_16x16x32_bf16 v[10:13], v[160:163], v[210:213], v[10:13]
	v_mfma_f32_16x16x32_bf16 v[14:17], v[168:171], v[210:213], v[14:17]
	v_mfma_f32_16x16x32_bf16 v[62:65], v[164:167], v[184:187], v[62:65]
	v_mfma_f32_16x16x32_bf16 v[58:61], v[172:175], v[184:187], v[58:61]
	v_mfma_f32_16x16x32_bf16 v[46:49], v[164:167], v[192:195], v[46:49]
	v_mfma_f32_16x16x32_bf16 v[42:45], v[172:175], v[192:195], v[42:45]
	s_barrier
	v_mfma_f32_16x16x32_bf16 v[30:33], v[164:167], v[206:209], v[30:33]
	v_mfma_f32_16x16x32_bf16 v[26:29], v[172:175], v[206:209], v[26:29]
	v_mfma_f32_16x16x32_bf16 v[10:13], v[164:167], v[214:217], v[10:13]
	v_mfma_f32_16x16x32_bf16 v[14:17], v[172:175], v[214:217], v[14:17]
	s_setprio 0
	s_add_i32 s85, s85, 2
	s_add_u32 s46, s46, 0x100
	s_addc_u32 s47, s47, 0
	s_add_u32 s83, s83, 0x100
	s_addc_u32 s84, s84, 0
	s_cmp_gt_u32 s85, 13
	s_cbranch_scc0 .LBB0_132
	s_and_b64 vcc, exec, s[10:11]
	s_cbranch_vccz .LBB0_135
	s_barrier

; #define PG8_STAGE(bufoff, gbase, voff) do { _Pragma("unroll") for (int _i = 0; _i < 2; ++_i) \
;         __builtin_amdgcn_global_load_lds((const unsigned*)((const char*)(gbase) + (voff)[_i]), (PG8_LAS unsigned*)(lds + (bufoff) + ldsw + _i * 8192), 16, 0, 0); } while (0)
; #define PG8_LDA(dst, b, h) do { _Pragma("unroll") for (int m = 0; m < 4; ++m) _Pragma("unroll") for (int k = 0; k < 2; ++k) dst[m][k] = *(const PG8_LAS bf16x8*)(lds + PG8_SA(b, h) + aoff + m * 2048 + k * 1024); } while (0)
; #define PG8_LDB(dst, b, h) do { _Pragma("unroll") for (int n = 0; n < 2; ++n) _Pragma("unroll") for (int k = 0; k < 2; ++k) dst[n][k] = *(const PG8_LAS bf16x8*)(lds + PG8_SB(b, h) + boff + n * 2048 + k * 1024); } while (0)
; #define PG8_MMA(ai, bj, At, Bt) do { __builtin_amdgcn_s_setprio(1); _Pragma("unroll") for (int m = 0; m < 4; ++m) _Pragma("unroll") for (int n = 0; n < 2; ++n) _Pragma("unroll") for (int k = 0; k < 2; ++k) \
;         acc[ai][bj][m][n] = __builtin_amdgcn_mfma_f32_16x16x32_bf16(Bt[n][k], At[m][k], acc[ai][bj][m][n], 0, 0, 0); __builtin_amdgcn_s_setprio(0); } while (0)
; #define PG8_WAIT_V(n) asm volatile("s_waitcnt vmcnt(" #n ")" ::: "memory")
; #define PG8_WAIT_L(n) asm volatile("s_waitcnt lgkmcnt(" #n ")" ::: "memory")
; #define PG8_BAR __builtin_amdgcn_s_barrier()
; #define PG8_SCHED __builtin_amdgcn_sched_barrier(0)
; template <class Epi, class Sched, bool ALIGN_EPI = false, bool SP2 = false>
; __device__ __forceinline__ void gemm_phase(PG8_LAS unsigned char* lds, const Gemm g, const Sched& S, const Epi& E) {
;     ...
;             PG8_LDB(B0, 0, 0); PG8_LDB(B1, 0, 1); PG8_SCHED; PG8_LDA(At, 0, 0); PG8_STAGE(PG8_SA(1, 1), a1 + hstep, voffA);
;             PG8_WAIT_V(8); PG8_WAIT_L(0); PG8_BAR; PG8_MMA(0, 0, At, B0); PG8_MMA(0, 1, At, B1); PG8_BAR; PG8_SCHED;
;             PG8_LDA(At, 0, 1); PG8_STAGE(PG8_SB(0, 0), b2, voffB); PG8_STAGE(PG8_SB(0, 1), b2 + hstep, voffB); PG8_STAGE(PG8_SA(0, 0), a2, voffA);
.LBB0_220:
	s_add_u32 s18, s60, 0xfffc0080
	s_addc_u32 s38, s61, -1
	s_add_i32 s39, 0, 0x10000
	s_cmp_eq_u32 s82, 12
	s_cselect_b32 s65, s47, s38
	s_cselect_b32 s64, s78, s18
	v_add_u32_e32 v145, s39, v141
	s_cselect_b32 s57, s49, s81
	s_cselect_b32 s56, s79, s80
	s_add_i32 s18, 0, 0x14000
	ds_read_b128 v[146:149], v145
	ds_read_b128 v[150:153], v145 offset:1024
	ds_read_b128 v[154:157], v145 offset:2048
	ds_read_b128 v[158:161], v145 offset:3072
	v_add_u32_e32 v145, s18, v141
	ds_read_b128 v[162:165], v145
	ds_read_b128 v[166:169], v145 offset:1024
	ds_read_b128 v[170:173], v145 offset:2048
	ds_read_b128 v[174:177], v145 offset:3072
	v_lshl_add_u64 v[194:195], s[60:61], 0, v[136:137]
	s_add_i32 m0, s29, 0xc000
	ds_read_b128 v[178:181], v144
	ds_read_b128 v[182:185], v144 offset:1024
	ds_read_b128 v[186:189], v144 offset:2048
	ds_read_b128 v[190:193], v144 offset:3072
	ds_read_b128 v[202:205], v144 offset:4096
	ds_read_b128 v[206:209], v144 offset:5120
	ds_read_b128 v[210:213], v144 offset:6144
	ds_read_b128 v[214:217], v144 offset:7168
	global_load_lds_dwordx4 v[194:195], off
	v_lshl_add_u64 v[194:195], s[60:61], 0, v[138:139]
	s_add_i32 m0, s29, 0xe000
	s_nop 0
	global_load_lds_dwordx4 v[194:195], off
	s_waitcnt vmcnt(8)
	s_waitcnt lgkmcnt(0)
	s_barrier
	s_setprio 1
	s_waitcnt lgkmcnt(0)
	v_mfma_f32_16x16x32_bf16 v[114:117], v[146:149], v[178:181], v[114:117]
	v_mfma_f32_16x16x32_bf16 v[118:121], v[154:157], v[178:181], v[118:121]
	v_mfma_f32_16x16x32_bf16 v[98:101], v[146:149], v[186:189], v[98:101]
	v_mfma_f32_16x16x32_bf16 v[102:105], v[154:157], v[186:189], v[102:105]
	v_mfma_f32_16x16x32_bf16 v[82:85], v[146:149], v[202:205], v[82:85]
	v_mfma_f32_16x16x32_bf16 v[86:89], v[154:157], v[202:205], v[86:89]
	v_mfma_f32_16x16x32_bf16 v[66:69], v[146:149], v[210:213], v[66:69]
	v_mfma_f32_16x16x32_bf16 v[70:73], v[154:157], v[210:213], v[70:73]
	v_mfma_f32_16x16x32_bf16 v[114:117], v[150:153], v[182:185], v[114:117]
	v_mfma_f32_16x16x32_bf16 v[118:121], v[158:161], v[182:185], v[118:121]
	v_mfma_f32_16x16x32_bf16 v[98:101], v[150:153], v[190:193], v[98:101]
	v_mfma_f32_16x16x32_bf16 v[102:105], v[158:161], v[190:193], v[102:105]
	v_mfma_f32_16x16x32_bf16 v[82:85], v[150:153], v[206:209], v[82:85]
	v_mfma_f32_16x16x32_bf16 v[86:89], v[158:161], v[206:209], v[86:89]
	v_mfma_f32_16x16x32_bf16 v[66:69], v[150:153], v[214:217], v[66:69]
	v_mfma_f32_16x16x32_bf16 v[70:73], v[158:161], v[214:217], v[70:73]
	s_setprio 0
	s_setprio 1
	v_mfma_f32_16x16x32_bf16 v[122:125], v[162:165], v[178:181], v[122:125]
	v_mfma_f32_16x16x32_bf16 v[126:129], v[170:173], v[178:181], v[126:129]
	v_mfma_f32_16x16x32_bf16 v[106:109], v[162:165], v[186:189], v[106:109]
	v_mfma_f32_16x16x32_bf16 v[110:113], v[170:173], v[186:189], v[110:113]
	v_mfma_f32_16x16x32_bf16 v[90:93], v[162:165], v[202:205], v[90:93]
	v_mfma_f32_16x16x32_bf16 v[94:97], v[170:173], v[202:205], v[94:97]
	v_mfma_f32_16x16x32_bf16 v[74:77], v[162:165], v[210:213], v[74:77]
	v_mfma_f32_16x16x32_bf16 v[78:81], v[170:173], v[210:213], v[78:81]
	v_mfma_f32_16x16x32_bf16 v[122:125], v[166:169], v[182:185], v[122:125]
	v_mfma_f32_16x16x32_bf16 v[126:129], v[174:177], v[182:185], v[126:129]
	v_mfma_f32_16x16x32_bf16 v[106:109], v[166:169], v[190:193], v[106:109]
	v_mfma_f32_16x16x32_bf16 v[110:113], v[174:177], v[190:193], v[110:113]
	s_barrier
	v_mfma_f32_16x16x32_bf16 v[90:93], v[166:169], v[206:209], v[90:93]
	v_mfma_f32_16x16x32_bf16 v[94:97], v[174:177], v[206:209], v[94:97]
	v_mfma_f32_16x16x32_bf16 v[74:77], v[166:169], v[214:217], v[74:77]
	v_mfma_f32_16x16x32_bf16 v[78:81], v[174:177], v[214:217], v[78:81]
	s_setprio 0
	s_add_i32 s38, s39, s27
	v_lshl_add_u64 v[194:195], s[56:57], 0, v[0:1]
	s_mov_b32 m0, s38
	ds_read_b128 v[178:181], v144 offset:16384
	ds_read_b128 v[182:185], v144 offset:17408
	ds_read_b128 v[186:189], v144 offset:18432
	ds_read_b128 v[190:193], v144 offset:19456
	ds_read_b128 v[202:205], v144 offset:20480
	ds_read_b128 v[206:209], v144 offset:21504
	ds_read_b128 v[210:213], v144 offset:22528
	ds_read_b128 v[214:217], v144 offset:23552
	global_load_lds_dwordx4 v[194:195], off
	s_add_i32 m0, s38, 0x2000
	s_add_u32 s38, s56, 0x40000
	v_lshl_add_u64 v[218:219], s[56:57], 0, v[130:131]
	s_addc_u32 s39, s57, 0
	s_add_i32 s18, s18, s27
	global_load_lds_dwordx4 v[218:219], off
	v_lshl_add_u64 v[220:221], s[38:39], 0, v[0:1]
	s_mov_b32 m0, s18
	v_lshl_add_u64 v[222:223], s[64:65], 0, v[132:133]
	global_load_lds_dwordx4 v[220:221], off
	v_lshl_add_u64 v[220:221], s[38:39], 0, v[130:131]
	s_add_i32 m0, s18, 0x2000
	s_nop 0
	global_load_lds_dwordx4 v[220:221], off
	v_lshl_add_u64 v[220:221], s[64:65], 0, v[134:135]
	s_mov_b32 m0, s29
	s_nop 0
	global_load_lds_dwordx4 v[220:221], off
	s_mov_b32 m0, s33
	s_nop 0
	global_load_lds_dwordx4 v[222:223], off
	s_waitcnt vmcnt(8)
	s_waitcnt lgkmcnt(0)
	s_barrier
; #define PG8_STAGE(bufoff, gbase, voff) do { _Pragma("unroll") for (int _i = 0; _i < 2; ++_i) \
;         __builtin_amdgcn_global_load_lds((const unsigned*)((const char*)(gbase) + (voff)[_i]), (PG8_LAS unsigned*)(lds + (bufoff) + ldsw + _i * 8192), 16, 0, 0); } while (0)
; #define PG8_LDA(dst, b, h) do { _Pragma("unroll") for (int m = 0; m < 4; ++m) _Pragma("unroll") for (int k = 0; k < 2; ++k) dst[m][k] = *(const PG8_LAS bf16x8*)(lds + PG8_SA(b, h) + aoff + m * 2048 + k * 1024); } while (0)
; #define PG8_LDB(dst, b, h) do { _Pragma("unroll") for (int n = 0; n < 2; ++n) _Pragma("unroll") for (int k = 0; k < 2; ++k) dst[n][k] = *(const PG8_LAS bf16x8*)(lds + PG8_SB(b, h) + boff + n * 2048 + k * 1024); } while (0)
; #define PG8_MMA(ai, bj, At, Bt) do { __builtin_amdgcn_s_setprio(1); _Pragma("unroll") for (int m = 0; m < 4; ++m) _Pragma("unroll") for (int n = 0; n < 2; ++n) _Pragma("unroll") for (int k = 0; k < 2; ++k) \
;         acc[ai][bj][m][n] = __builtin_amdgcn_mfma_f32_16x16x32_bf16(Bt[n][k], At[m][k], acc[ai][bj][m][n], 0, 0, 0); __builtin_amdgcn_s_setprio(0); } while (0)
; #define PG8_WAIT_V(n) asm volatile("s_waitcnt vmcnt(" #n ")" ::: "memory")
; #define PG8_WAIT_L(n) asm volatile("s_waitcnt lgkmcnt(" #n ")" ::: "memory")
; #define PG8_BAR __builtin_amdgcn_s_barrier()
; #define PG8_SCHED __builtin_amdgcn_sched_barrier(0)
; template <class Epi, class Sched, bool ALIGN_EPI = false, bool SP2 = false>
; __device__ __forceinline__ void gemm_phase(PG8_LAS unsigned char* lds, const Gemm g, const Sched& S, const Epi& E) {
;     ...
;             PG8_WAIT_V(8); PG8_WAIT_L(0); PG8_BAR; PG8_MMA(1, 0, At, B0); PG8_MMA(1, 1, At, B1); PG8_BAR; PG8_SCHED;
;             PG8_LDB(B0, 1, 0); PG8_LDB(B1, 1, 1); PG8_SCHED; PG8_LDA(At, 1, 0); PG8_STAGE(PG8_SA(0, 1), a2 + hstep, voffA);
;             PG8_WAIT_V(8); PG8_WAIT_L(0); PG8_BAR; PG8_MMA(0, 0, At, B0); PG8_MMA(0, 1, At, B1); PG8_BAR; PG8_SCHED;
	s_setprio 1
	s_waitcnt lgkmcnt(0)
	v_mfma_f32_16x16x32_bf16 v[50:53], v[146:149], v[178:181], v[50:53]
	v_mfma_f32_16x16x32_bf16 v[54:57], v[154:157], v[178:181], v[54:57]
	v_mfma_f32_16x16x32_bf16 v[34:37], v[146:149], v[186:189], v[34:37]
	v_mfma_f32_16x16x32_bf16 v[38:41], v[154:157], v[186:189], v[38:41]
	v_mfma_f32_16x16x32_bf16 v[18:21], v[146:149], v[202:205], v[18:21]
	v_mfma_f32_16x16x32_bf16 v[22:25], v[154:157], v[202:205], v[22:25]
	v_mfma_f32_16x16x32_bf16 v[2:5], v[146:149], v[210:213], v[2:5]
	v_mfma_f32_16x16x32_bf16 v[6:9], v[154:157], v[210:213], v[6:9]
	v_mfma_f32_16x16x32_bf16 v[50:53], v[150:153], v[182:185], v[50:53]
	v_mfma_f32_16x16x32_bf16 v[54:57], v[158:161], v[182:185], v[54:57]
	v_mfma_f32_16x16x32_bf16 v[34:37], v[150:153], v[190:193], v[34:37]
	v_mfma_f32_16x16x32_bf16 v[38:41], v[158:161], v[190:193], v[38:41]
	v_mfma_f32_16x16x32_bf16 v[18:21], v[150:153], v[206:209], v[18:21]
	v_mfma_f32_16x16x32_bf16 v[22:25], v[158:161], v[206:209], v[22:25]
	v_mfma_f32_16x16x32_bf16 v[2:5], v[150:153], v[214:217], v[2:5]
	v_mfma_f32_16x16x32_bf16 v[6:9], v[158:161], v[214:217], v[6:9]
	s_setprio 0
	s_setprio 1
	v_mfma_f32_16x16x32_bf16 v[58:61], v[162:165], v[178:181], v[58:61]
	v_mfma_f32_16x16x32_bf16 v[62:65], v[170:173], v[178:181], v[62:65]
	v_mfma_f32_16x16x32_bf16 v[42:45], v[162:165], v[186:189], v[42:45]
	v_mfma_f32_16x16x32_bf16 v[46:49], v[170:173], v[186:189], v[46:49]
	v_mfma_f32_16x16x32_bf16 v[26:29], v[162:165], v[202:205], v[26:29]
	v_mfma_f32_16x16x32_bf16 v[30:33], v[170:173], v[202:205], v[30:33]
	v_mfma_f32_16x16x32_bf16 v[10:13], v[162:165], v[210:213], v[10:13]
	v_mfma_f32_16x16x32_bf16 v[14:17], v[170:173], v[210:213], v[14:17]
	v_mfma_f32_16x16x32_bf16 v[58:61], v[166:169], v[182:185], v[58:61]
	v_mfma_f32_16x16x32_bf16 v[62:65], v[174:177], v[182:185], v[62:65]
	v_mfma_f32_16x16x32_bf16 v[42:45], v[166:169], v[190:193], v[42:45]
	v_mfma_f32_16x16x32_bf16 v[46:49], v[174:177], v[190:193], v[46:49]
	s_barrier
	v_mfma_f32_16x16x32_bf16 v[26:29], v[166:169], v[206:209], v[26:29]
	v_mfma_f32_16x16x32_bf16 v[30:33], v[174:177], v[206:209], v[30:33]
	v_mfma_f32_16x16x32_bf16 v[10:13], v[166:169], v[214:217], v[10:13]
	v_mfma_f32_16x16x32_bf16 v[14:17], v[174:177], v[214:217], v[14:17]
	s_setprio 0
	s_add_i32 s18, 0, 0x18000
	v_add_u32_e32 v145, s18, v141
	s_add_i32 s83, 0, 0x1c000
	ds_read_b128 v[146:149], v145
	ds_read_b128 v[150:153], v145 offset:1024
	ds_read_b128 v[154:157], v145 offset:2048
	ds_read_b128 v[158:161], v145 offset:3072
	v_add_u32_e32 v145, s83, v141
	ds_read_b128 v[162:165], v145
	ds_read_b128 v[166:169], v145 offset:1024
	ds_read_b128 v[170:173], v145 offset:2048
	ds_read_b128 v[174:177], v145 offset:3072
	s_add_u32 s38, s64, 0x40000
	s_addc_u32 s39, s65, 0
	s_mov_b32 m0, s58
	v_lshl_add_u64 v[224:225], s[38:39], 0, v[134:135]
	ds_read_b128 v[178:181], v144 offset:32768
	ds_read_b128 v[182:185], v144 offset:33792
	ds_read_b128 v[186:189], v144 offset:34816
	ds_read_b128 v[190:193], v144 offset:35840
	ds_read_b128 v[202:205], v144 offset:36864
	ds_read_b128 v[206:209], v144 offset:37888
	ds_read_b128 v[210:213], v144 offset:38912
	ds_read_b128 v[214:217], v144 offset:39936
	global_load_lds_dwordx4 v[224:225], off
	v_lshl_add_u64 v[224:225], s[38:39], 0, v[132:133]
	s_mov_b32 m0, s69
	s_nop 0
	global_load_lds_dwordx4 v[224:225], off
	s_waitcnt vmcnt(8)
	s_waitcnt lgkmcnt(0)
	s_barrier
	s_setprio 1
	s_waitcnt lgkmcnt(0)
	v_mfma_f32_16x16x32_bf16 v[114:117], v[146:149], v[178:181], v[114:117]
	v_mfma_f32_16x16x32_bf16 v[118:121], v[154:157], v[178:181], v[118:121]
	v_mfma_f32_16x16x32_bf16 v[98:101], v[146:149], v[186:189], v[98:101]
	v_mfma_f32_16x16x32_bf16 v[102:105], v[154:157], v[186:189], v[102:105]
	v_mfma_f32_16x16x32_bf16 v[82:85], v[146:149], v[202:205], v[82:85]
	v_mfma_f32_16x16x32_bf16 v[86:89], v[154:157], v[202:205], v[86:89]
	v_mfma_f32_16x16x32_bf16 v[66:69], v[146:149], v[210:213], v[66:69]
	v_mfma_f32_16x16x32_bf16 v[70:73], v[154:157], v[210:213], v[70:73]
	v_mfma_f32_16x16x32_bf16 v[114:117], v[150:153], v[182:185], v[114:117]
	v_mfma_f32_16x16x32_bf16 v[118:121], v[158:161], v[182:185], v[118:121]
	v_mfma_f32_16x16x32_bf16 v[98:101], v[150:153], v[190:193], v[98:101]
	v_mfma_f32_16x16x32_bf16 v[102:105], v[158:161], v[190:193], v[102:105]
	v_mfma_f32_16x16x32_bf16 v[82:85], v[150:153], v[206:209], v[82:85]
	v_mfma_f32_16x16x32_bf16 v[86:89], v[158:161], v[206:209], v[86:89]
	v_mfma_f32_16x16x32_bf16 v[66:69], v[150:153], v[214:217], v[66:69]
	v_mfma_f32_16x16x32_bf16 v[70:73], v[158:161], v[214:217], v[70:73]
	s_setprio 0
	s_setprio 1
	v_mfma_f32_16x16x32_bf16 v[122:125], v[162:165], v[178:181], v[122:125]
	v_mfma_f32_16x16x32_bf16 v[126:129], v[170:173], v[178:181], v[126:129]
	v_mfma_f32_16x16x32_bf16 v[106:109], v[162:165], v[186:189], v[106:109]
	v_mfma_f32_16x16x32_bf16 v[110:113], v[170:173], v[186:189], v[110:113]
	v_mfma_f32_16x16x32_bf16 v[90:93], v[162:165], v[202:205], v[90:93]
	v_mfma_f32_16x16x32_bf16 v[94:97], v[170:173], v[202:205], v[94:97]
	v_mfma_f32_16x16x32_bf16 v[74:77], v[162:165], v[210:213], v[74:77]
	v_mfma_f32_16x16x32_bf16 v[78:81], v[170:173], v[210:213], v[78:81]
	v_mfma_f32_16x16x32_bf16 v[122:125], v[166:169], v[182:185], v[122:125]
	v_mfma_f32_16x16x32_bf16 v[126:129], v[174:177], v[182:185], v[126:129]
	v_mfma_f32_16x16x32_bf16 v[106:109], v[166:169], v[190:193], v[106:109]
	v_mfma_f32_16x16x32_bf16 v[110:113], v[174:177], v[190:193], v[110:113]
	s_barrier
; #define PG8_STAGE(bufoff, gbase, voff) do { _Pragma("unroll") for (int _i = 0; _i < 2; ++_i) \
;         __builtin_amdgcn_global_load_lds((const unsigned*)((const char*)(gbase) + (voff)[_i]), (PG8_LAS unsigned*)(lds + (bufoff) + ldsw + _i * 8192), 16, 0, 0); } while (0)
; #define PG8_LDA(dst, b, h) do { _Pragma("unroll") for (int m = 0; m < 4; ++m) _Pragma("unroll") for (int k = 0; k < 2; ++k) dst[m][k] = *(const PG8_LAS bf16x8*)(lds + PG8_SA(b, h) + aoff + m * 2048 + k * 1024); } while (0)
; #define PG8_MMA(ai, bj, At, Bt) do { __builtin_amdgcn_s_setprio(1); _Pragma("unroll") for (int m = 0; m < 4; ++m) _Pragma("unroll") for (int n = 0; n < 2; ++n) _Pragma("unroll") for (int k = 0; k < 2; ++k) \
;         acc[ai][bj][m][n] = __builtin_amdgcn_mfma_f32_16x16x32_bf16(Bt[n][k], At[m][k], acc[ai][bj][m][n], 0, 0, 0); __builtin_amdgcn_s_setprio(0); } while (0)
; #define PG8_WAIT_V(n) asm volatile("s_waitcnt vmcnt(" #n ")" ::: "memory")
; #define PG8_WAIT_L(n) asm volatile("s_waitcnt lgkmcnt(" #n ")" ::: "memory")
; #define PG8_BAR __builtin_amdgcn_s_barrier()
; #define PG8_SCHED __builtin_amdgcn_sched_barrier(0)
; template <class Epi, class Sched, bool ALIGN_EPI = false, bool SP2 = false>
; __device__ __forceinline__ void gemm_phase(PG8_LAS unsigned char* lds, const Gemm g, const Sched& S, const Epi& E) {
;     ...
;             PG8_WAIT_V(8); PG8_WAIT_L(0); PG8_BAR; PG8_MMA(0, 0, At, B0); PG8_MMA(0, 1, At, B1); PG8_BAR; PG8_SCHED;
;             PG8_LDA(At, 1, 1); PG8_STAGE(PG8_SB(1, 0), b3, voffB); PG8_STAGE(PG8_SB(1, 1), b3 + hstep, voffB); PG8_STAGE(PG8_SA(1, 0), a3, voffA);
;             PG8_WAIT_V(8); PG8_WAIT_L(0); PG8_BAR; PG8_MMA(1, 0, At, B0); PG8_MMA(1, 1, At, B1); PG8_BAR; PG8_SCHED;
	v_mfma_f32_16x16x32_bf16 v[90:93], v[166:169], v[206:209], v[90:93]
	v_mfma_f32_16x16x32_bf16 v[94:97], v[174:177], v[206:209], v[94:97]
	v_mfma_f32_16x16x32_bf16 v[74:77], v[166:169], v[214:217], v[74:77]
	v_mfma_f32_16x16x32_bf16 v[78:81], v[174:177], v[214:217], v[78:81]
	s_setprio 0
	s_add_i32 s18, s18, s27
	v_lshl_add_u64 v[194:195], v[194:195], 0, s[30:31]
	s_mov_b32 m0, s18
	ds_read_b128 v[178:181], v144 offset:49152
	ds_read_b128 v[182:185], v144 offset:50176
	ds_read_b128 v[186:189], v144 offset:51200
	ds_read_b128 v[190:193], v144 offset:52224
	ds_read_b128 v[202:205], v144 offset:53248
	ds_read_b128 v[206:209], v144 offset:54272
	ds_read_b128 v[210:213], v144 offset:55296
	ds_read_b128 v[214:217], v144 offset:56320
	global_load_lds_dwordx4 v[194:195], off
	s_add_i32 m0, s18, 0x2000
	s_add_u32 s38, s56, 0x40080
	v_lshl_add_u64 v[194:195], v[218:219], 0, s[30:31]
	s_addc_u32 s39, s57, 0
	s_add_i32 s18, s83, s27
	global_load_lds_dwordx4 v[194:195], off
	v_lshl_add_u64 v[194:195], s[38:39], 0, v[0:1]
	s_mov_b32 m0, s18
	s_nop 0
	global_load_lds_dwordx4 v[194:195], off
	v_lshl_add_u64 v[194:195], s[38:39], 0, v[130:131]
	s_add_i32 m0, s18, 0x2000
	s_nop 0
	global_load_lds_dwordx4 v[194:195], off
	v_lshl_add_u64 v[194:195], v[220:221], 0, s[30:31]
	s_mov_b32 m0, s71
	s_nop 0
	global_load_lds_dwordx4 v[194:195], off
	v_lshl_add_u64 v[194:195], v[222:223], 0, s[30:31]
	s_mov_b32 m0, s72
	s_nop 0
	global_load_lds_dwordx4 v[194:195], off
	s_waitcnt vmcnt(8)
	s_waitcnt lgkmcnt(0)
	s_barrier
	s_setprio 1
	s_waitcnt lgkmcnt(0)
	v_mfma_f32_16x16x32_bf16 v[50:53], v[146:149], v[178:181], v[50:53]
	v_mfma_f32_16x16x32_bf16 v[54:57], v[154:157], v[178:181], v[54:57]
	v_mfma_f32_16x16x32_bf16 v[34:37], v[146:149], v[186:189], v[34:37]
	v_mfma_f32_16x16x32_bf16 v[38:41], v[154:157], v[186:189], v[38:41]
	v_mfma_f32_16x16x32_bf16 v[18:21], v[146:149], v[202:205], v[18:21]
	v_mfma_f32_16x16x32_bf16 v[22:25], v[154:157], v[202:205], v[22:25]
	v_mfma_f32_16x16x32_bf16 v[2:5], v[146:149], v[210:213], v[2:5]
	v_mfma_f32_16x16x32_bf16 v[6:9], v[154:157], v[210:213], v[6:9]
	v_mfma_f32_16x16x32_bf16 v[50:53], v[150:153], v[182:185], v[50:53]
	v_mfma_f32_16x16x32_bf16 v[54:57], v[158:161], v[182:185], v[54:57]
	v_mfma_f32_16x16x32_bf16 v[34:37], v[150:153], v[190:193], v[34:37]
	v_mfma_f32_16x16x32_bf16 v[38:41], v[158:161], v[190:193], v[38:41]
	v_mfma_f32_16x16x32_bf16 v[18:21], v[150:153], v[206:209], v[18:21]
	v_mfma_f32_16x16x32_bf16 v[22:25], v[158:161], v[206:209], v[22:25]
	v_mfma_f32_16x16x32_bf16 v[2:5], v[150:153], v[214:217], v[2:5]
	v_mfma_f32_16x16x32_bf16 v[6:9], v[158:161], v[214:217], v[6:9]
	s_setprio 0
	s_setprio 1
	v_mfma_f32_16x16x32_bf16 v[58:61], v[162:165], v[178:181], v[58:61]
	v_mfma_f32_16x16x32_bf16 v[62:65], v[170:173], v[178:181], v[62:65]
	v_mfma_f32_16x16x32_bf16 v[42:45], v[162:165], v[186:189], v[42:45]
	v_mfma_f32_16x16x32_bf16 v[46:49], v[170:173], v[186:189], v[46:49]
	v_mfma_f32_16x16x32_bf16 v[26:29], v[162:165], v[202:205], v[26:29]
	v_mfma_f32_16x16x32_bf16 v[30:33], v[170:173], v[202:205], v[30:33]
	v_mfma_f32_16x16x32_bf16 v[10:13], v[162:165], v[210:213], v[10:13]
	v_mfma_f32_16x16x32_bf16 v[14:17], v[170:173], v[210:213], v[14:17]
	v_mfma_f32_16x16x32_bf16 v[58:61], v[166:169], v[182:185], v[58:61]
	v_mfma_f32_16x16x32_bf16 v[62:65], v[174:177], v[182:185], v[62:65]
	v_mfma_f32_16x16x32_bf16 v[42:45], v[166:169], v[190:193], v[42:45]
	v_mfma_f32_16x16x32_bf16 v[46:49], v[174:177], v[190:193], v[46:49]
	s_barrier
	v_mfma_f32_16x16x32_bf16 v[26:29], v[166:169], v[206:209], v[26:29]
	v_mfma_f32_16x16x32_bf16 v[30:33], v[174:177], v[206:209], v[30:33]
	v_mfma_f32_16x16x32_bf16 v[10:13], v[166:169], v[214:217], v[10:13]
	v_mfma_f32_16x16x32_bf16 v[14:17], v[174:177], v[214:217], v[14:17]
	s_setprio 0
	s_add_i32 s82, s82, 2
	s_add_u32 s60, s60, 0x100
	s_addc_u32 s61, s61, 0
	s_add_u32 s80, s80, 0x100
	s_addc_u32 s81, s81, 0
	s_cmp_gt_u32 s82, 13
	s_cbranch_scc0 .LBB0_220
	s_and_b64 vcc, exec, s[44:45]
	s_cbranch_vccz .LBB0_223
	s_barrier

; #define PG8_STAGE(bufoff, gbase, voff) do { _Pragma("unroll") for (int _i = 0; _i < 2; ++_i) \
;         __builtin_amdgcn_global_load_lds((const unsigned*)((const char*)(gbase) + (voff)[_i]), (PG8_LAS unsigned*)(lds + (bufoff) + ldsw + _i * 8192), 16, 0, 0); } while (0)
; #define PG8_LDA(dst, b, h) do { _Pragma("unroll") for (int m = 0; m < 4; ++m) _Pragma("unroll") for (int k = 0; k < 2; ++k) dst[m][k] = *(const PG8_LAS bf16x8*)(lds + PG8_SA(b, h) + aoff + m * 2048 + k * 1024); } while (0)
; #define PG8_LDB(dst, b, h) do { _Pragma("unroll") for (int n = 0; n < 2; ++n) _Pragma("unroll") for (int k = 0; k < 2; ++k) dst[n][k] = *(const PG8_LAS bf16x8*)(lds + PG8_SB(b, h) + boff + n * 2048 + k * 1024); } while (0)
; #define PG8_MMA(ai, bj, At, Bt) do { __builtin_amdgcn_s_setprio(1); _Pragma("unroll") for (int m = 0; m < 4; ++m) _Pragma("unroll") for (int n = 0; n < 2; ++n) _Pragma("unroll") for (int k = 0; k < 2; ++k) \
;         acc[ai][bj][m][n] = __builtin_amdgcn_mfma_f32_16x16x32_bf16(Bt[n][k], At[m][k], acc[ai][bj][m][n], 0, 0, 0); __builtin_amdgcn_s_setprio(0); } while (0)
; #define PG8_WAIT_V(n) asm volatile("s_waitcnt vmcnt(" #n ")" ::: "memory")
; #define PG8_WAIT_L(n) asm volatile("s_waitcnt lgkmcnt(" #n ")" ::: "memory")
; #define PG8_BAR __builtin_amdgcn_s_barrier()
; #define PG8_SCHED __builtin_amdgcn_sched_barrier(0)
; template <class Epi, class Sched, bool ALIGN_EPI = false, bool SP2 = false>
; __device__ __forceinline__ void gemm_phase(PG8_LAS unsigned char* lds, const Gemm g, const Sched& S, const Epi& E) {
;     ...
;         for (int t = 0; t < nt; t += 2) {
;             const bool last = (t == nt - 2);
;             const char* a1 = cA + (size_t)(t + 1) * kstep;
;             const char* a2 = last ? nA : cA + (size_t)(t + 2) * kstep; const char* b2 = last ? nB : cB + (size_t)(t + 2) * kstep;
;             const char* a3 = a2 + kstep; const char* b3 = b2 + kstep;
;             if (last && has_next) S.a_ready(nxt);
;             if constexpr (SP2) {
;             PG8_LDB(B0, 0, 0); PG8_LDB(B1, 0, 1); PG8_SCHED; PG8_LDA(At, 0, 0); PG8_STAGE(PG8_SA(1, 1), a1 + hstep, voffA);
;             PG8_WAIT_V(8); PG8_WAIT_L(0); PG8_BAR; PG8_MMA(0, 0, At, B0); PG8_MMA(0, 1, At, B1); PG8_BAR; PG8_SCHED;
;             PG8_LDA(At, 0, 1); PG8_STAGE(PG8_SB(0, 0), b2, voffB); PG8_STAGE(PG8_SB(0, 1), b2 + hstep, voffB); PG8_STAGE(PG8_SA(0, 0), a2, voffA);
.LBB0_274:
	s_add_i32 vcc_lo, s46, 2
	s_add_u32 s38, s48, 0x80
	s_addc_u32 s39, s49, 0
	s_add_i32 vcc_hi, 0, 0x10000
	s_cmp_eq_u32 s99, s46
	s_cselect_b32 s47, s81, s39
	s_cselect_b32 s46, s80, s38
	s_cselect_b32 s39, s83, s51
	s_cselect_b32 s38, s82, s50
	s_add_i32 s18, 0, 0x14000
	v_add_u32_e32 v142, vcc_hi, v245
	v_add_u32_e32 v158, s18, v245
	ds_read_b128 v[110:113], v142
	ds_read_b128 v[118:121], v142 offset:1024
	ds_read_b128 v[138:141], v142 offset:2048
	ds_read_b128 v[142:145], v142 offset:3072
	ds_read_b128 v[146:149], v158
	ds_read_b128 v[150:153], v158 offset:1024
	ds_read_b128 v[154:157], v158 offset:2048
	ds_read_b128 v[158:161], v158 offset:3072
	v_lshl_add_u64 v[210:211], s[48:49], 0, v[206:207]
	s_add_i32 m0, s92, 0xc000
	ds_read_b128 v[162:165], v247
	ds_read_b128 v[166:169], v247 offset:1024
	ds_read_b128 v[170:173], v247 offset:2048
	ds_read_b128 v[174:177], v247 offset:3072
	ds_read_b128 v[178:181], v247 offset:4096
	ds_read_b128 v[182:185], v247 offset:5120
	ds_read_b128 v[186:189], v247 offset:6144
	ds_read_b128 v[190:193], v247 offset:7168
	global_load_lds_dwordx4 v[210:211], off
	v_lshl_add_u64 v[210:211], s[48:49], 0, v[208:209]
	s_add_i32 m0, s92, 0xe000
	s_nop 0
	global_load_lds_dwordx4 v[210:211], off
	s_waitcnt vmcnt(8)
	s_waitcnt lgkmcnt(0)
	s_barrier
	s_setprio 1
	s_waitcnt lgkmcnt(0)
	v_mfma_f32_16x16x32_bf16 v[130:133], v[110:113], v[162:165], v[130:133]
	v_mfma_f32_16x16x32_bf16 v[134:137], v[138:141], v[162:165], v[134:137]
	v_mfma_f32_16x16x32_bf16 v[114:117], v[110:113], v[170:173], v[114:117]
	v_mfma_f32_16x16x32_bf16 v[106:109], v[138:141], v[170:173], v[106:109]
	v_mfma_f32_16x16x32_bf16 v[94:97], v[110:113], v[178:181], v[94:97]
	v_mfma_f32_16x16x32_bf16 v[90:93], v[138:141], v[178:181], v[90:93]
	v_mfma_f32_16x16x32_bf16 v[78:81], v[110:113], v[186:189], v[78:81]
	v_mfma_f32_16x16x32_bf16 v[74:77], v[138:141], v[186:189], v[74:77]
	v_mfma_f32_16x16x32_bf16 v[130:133], v[118:121], v[166:169], v[130:133]
	v_mfma_f32_16x16x32_bf16 v[134:137], v[142:145], v[166:169], v[134:137]
	v_mfma_f32_16x16x32_bf16 v[114:117], v[118:121], v[174:177], v[114:117]
	v_mfma_f32_16x16x32_bf16 v[106:109], v[142:145], v[174:177], v[106:109]
	v_mfma_f32_16x16x32_bf16 v[94:97], v[118:121], v[182:185], v[94:97]
	v_mfma_f32_16x16x32_bf16 v[90:93], v[142:145], v[182:185], v[90:93]
	v_mfma_f32_16x16x32_bf16 v[78:81], v[118:121], v[190:193], v[78:81]
	v_mfma_f32_16x16x32_bf16 v[74:77], v[142:145], v[190:193], v[74:77]
	s_setprio 0
	s_setprio 1
	v_mfma_f32_16x16x32_bf16 v[126:129], v[146:149], v[162:165], v[126:129]
	v_mfma_f32_16x16x32_bf16 v[122:125], v[154:157], v[162:165], v[122:125]
	v_mfma_f32_16x16x32_bf16 v[102:105], v[146:149], v[170:173], v[102:105]
	v_mfma_f32_16x16x32_bf16 v[98:101], v[154:157], v[170:173], v[98:101]
	v_mfma_f32_16x16x32_bf16 v[86:89], v[146:149], v[178:181], v[86:89]
	v_mfma_f32_16x16x32_bf16 v[82:85], v[154:157], v[178:181], v[82:85]
	v_mfma_f32_16x16x32_bf16 v[70:73], v[146:149], v[186:189], v[70:73]
	v_mfma_f32_16x16x32_bf16 v[66:69], v[154:157], v[186:189], v[66:69]
	v_mfma_f32_16x16x32_bf16 v[126:129], v[150:153], v[166:169], v[126:129]
	v_mfma_f32_16x16x32_bf16 v[122:125], v[158:161], v[166:169], v[122:125]
	v_mfma_f32_16x16x32_bf16 v[102:105], v[150:153], v[174:177], v[102:105]
	v_mfma_f32_16x16x32_bf16 v[98:101], v[158:161], v[174:177], v[98:101]
	s_barrier
	v_mfma_f32_16x16x32_bf16 v[86:89], v[150:153], v[182:185], v[86:89]
	v_mfma_f32_16x16x32_bf16 v[82:85], v[158:161], v[182:185], v[82:85]
	v_mfma_f32_16x16x32_bf16 v[70:73], v[150:153], v[190:193], v[70:73]
	v_mfma_f32_16x16x32_bf16 v[66:69], v[158:161], v[190:193], v[66:69]
	s_setprio 0
	s_add_i32 vcc_hi, vcc_hi, s6
	v_lshl_add_u64 v[210:211], s[38:39], 0, v[0:1]
	s_mov_b32 m0, vcc_hi
	ds_read_b128 v[162:165], v247 offset:16384
	ds_read_b128 v[166:169], v247 offset:17408
	ds_read_b128 v[170:173], v247 offset:18432
	ds_read_b128 v[174:177], v247 offset:19456
	ds_read_b128 v[178:181], v247 offset:20480
	ds_read_b128 v[182:185], v247 offset:21504
	ds_read_b128 v[186:189], v247 offset:22528
	ds_read_b128 v[190:193], v247 offset:23552
	global_load_lds_dwordx4 v[210:211], off
	s_add_i32 m0, vcc_hi, 0x2000
	v_lshl_add_u64 v[212:213], s[38:39], 0, v[204:205]
	s_add_u32 s38, s38, s58
	s_addc_u32 s39, s39, 0
	s_add_i32 s18, s18, s6
	global_load_lds_dwordx4 v[212:213], off
	v_lshl_add_u64 v[214:215], s[38:39], 0, v[0:1]
	s_mov_b32 m0, s18
	v_lshl_add_u64 v[216:217], s[38:39], 0, v[204:205]
	global_load_lds_dwordx4 v[214:215], off
	s_add_i32 m0, s18, 0x2000
	v_lshl_add_u64 v[218:219], s[46:47], 0, v[194:195]
	global_load_lds_dwordx4 v[216:217], off
	s_mov_b32 m0, s92
	v_lshl_add_u64 v[220:221], s[46:47], 0, v[202:203]
	global_load_lds_dwordx4 v[218:219], off
	s_mov_b32 m0, s93
	s_nop 0
	global_load_lds_dwordx4 v[220:221], off
	s_waitcnt vmcnt(8)
	s_waitcnt lgkmcnt(0)
	s_barrier
; #define PG8_STAGE(bufoff, gbase, voff) do { _Pragma("unroll") for (int _i = 0; _i < 2; ++_i) \
;         __builtin_amdgcn_global_load_lds((const unsigned*)((const char*)(gbase) + (voff)[_i]), (PG8_LAS unsigned*)(lds + (bufoff) + ldsw + _i * 8192), 16, 0, 0); } while (0)
; #define PG8_LDA(dst, b, h) do { _Pragma("unroll") for (int m = 0; m < 4; ++m) _Pragma("unroll") for (int k = 0; k < 2; ++k) dst[m][k] = *(const PG8_LAS bf16x8*)(lds + PG8_SA(b, h) + aoff + m * 2048 + k * 1024); } while (0)
; #define PG8_LDB(dst, b, h) do { _Pragma("unroll") for (int n = 0; n < 2; ++n) _Pragma("unroll") for (int k = 0; k < 2; ++k) dst[n][k] = *(const PG8_LAS bf16x8*)(lds + PG8_SB(b, h) + boff + n * 2048 + k * 1024); } while (0)
; #define PG8_MMA(ai, bj, At, Bt) do { __builtin_amdgcn_s_setprio(1); _Pragma("unroll") for (int m = 0; m < 4; ++m) _Pragma("unroll") for (int n = 0; n < 2; ++n) _Pragma("unroll") for (int k = 0; k < 2; ++k) \
;         acc[ai][bj][m][n] = __builtin_amdgcn_mfma_f32_16x16x32_bf16(Bt[n][k], At[m][k], acc[ai][bj][m][n], 0, 0, 0); __builtin_amdgcn_s_setprio(0); } while (0)
; #define PG8_WAIT_V(n) asm volatile("s_waitcnt vmcnt(" #n ")" ::: "memory")
; #define PG8_WAIT_L(n) asm volatile("s_waitcnt lgkmcnt(" #n ")" ::: "memory")
; #define PG8_BAR __builtin_amdgcn_s_barrier()
; #define PG8_SCHED __builtin_amdgcn_sched_barrier(0)
; template <class Epi, class Sched, bool ALIGN_EPI = false, bool SP2 = false>
; __device__ __forceinline__ void gemm_phase(PG8_LAS unsigned char* lds, const Gemm g, const Sched& S, const Epi& E) {
;     ...
;             PG8_WAIT_V(8); PG8_WAIT_L(0); PG8_BAR; PG8_MMA(1, 0, At, B0); PG8_MMA(1, 1, At, B1); PG8_BAR; PG8_SCHED;
;             PG8_LDB(B0, 1, 0); PG8_LDB(B1, 1, 1); PG8_SCHED; PG8_LDA(At, 1, 0); PG8_STAGE(PG8_SA(0, 1), a2 + hstep, voffA);
;             PG8_WAIT_V(8); PG8_WAIT_L(0); PG8_BAR; PG8_MMA(0, 0, At, B0); PG8_MMA(0, 1, At, B1); PG8_BAR; PG8_SCHED;
	s_setprio 1
	s_waitcnt lgkmcnt(0)
	v_mfma_f32_16x16x32_bf16 v[62:65], v[110:113], v[162:165], v[62:65]
	v_mfma_f32_16x16x32_bf16 v[58:61], v[138:141], v[162:165], v[58:61]
	v_mfma_f32_16x16x32_bf16 v[46:49], v[110:113], v[170:173], v[46:49]
	v_mfma_f32_16x16x32_bf16 v[42:45], v[138:141], v[170:173], v[42:45]
	v_mfma_f32_16x16x32_bf16 v[30:33], v[110:113], v[178:181], v[30:33]
	v_mfma_f32_16x16x32_bf16 v[26:29], v[138:141], v[178:181], v[26:29]
	v_mfma_f32_16x16x32_bf16 v[14:17], v[110:113], v[186:189], v[14:17]
	v_mfma_f32_16x16x32_bf16 v[10:13], v[138:141], v[186:189], v[10:13]
	v_mfma_f32_16x16x32_bf16 v[62:65], v[118:121], v[166:169], v[62:65]
	v_mfma_f32_16x16x32_bf16 v[58:61], v[142:145], v[166:169], v[58:61]
	v_mfma_f32_16x16x32_bf16 v[46:49], v[118:121], v[174:177], v[46:49]
	v_mfma_f32_16x16x32_bf16 v[42:45], v[142:145], v[174:177], v[42:45]
	v_mfma_f32_16x16x32_bf16 v[30:33], v[118:121], v[182:185], v[30:33]
	v_mfma_f32_16x16x32_bf16 v[26:29], v[142:145], v[182:185], v[26:29]
	v_mfma_f32_16x16x32_bf16 v[14:17], v[118:121], v[190:193], v[14:17]
	v_mfma_f32_16x16x32_bf16 v[10:13], v[142:145], v[190:193], v[10:13]
	s_setprio 0
	s_setprio 1
	v_mfma_f32_16x16x32_bf16 v[54:57], v[146:149], v[162:165], v[54:57]
	v_mfma_f32_16x16x32_bf16 v[50:53], v[154:157], v[162:165], v[50:53]
	v_mfma_f32_16x16x32_bf16 v[38:41], v[146:149], v[170:173], v[38:41]
	v_mfma_f32_16x16x32_bf16 v[34:37], v[154:157], v[170:173], v[34:37]
	v_mfma_f32_16x16x32_bf16 v[22:25], v[146:149], v[178:181], v[22:25]
	v_mfma_f32_16x16x32_bf16 v[18:21], v[154:157], v[178:181], v[18:21]
	v_mfma_f32_16x16x32_bf16 v[6:9], v[146:149], v[186:189], v[6:9]
	v_mfma_f32_16x16x32_bf16 v[2:5], v[154:157], v[186:189], v[2:5]
	v_mfma_f32_16x16x32_bf16 v[54:57], v[150:153], v[166:169], v[54:57]
	v_mfma_f32_16x16x32_bf16 v[50:53], v[158:161], v[166:169], v[50:53]
	v_mfma_f32_16x16x32_bf16 v[38:41], v[150:153], v[174:177], v[38:41]
	v_mfma_f32_16x16x32_bf16 v[34:37], v[158:161], v[174:177], v[34:37]
	s_barrier
	v_mfma_f32_16x16x32_bf16 v[22:25], v[150:153], v[182:185], v[22:25]
	v_mfma_f32_16x16x32_bf16 v[18:21], v[158:161], v[182:185], v[18:21]
	v_mfma_f32_16x16x32_bf16 v[6:9], v[150:153], v[190:193], v[6:9]
	v_mfma_f32_16x16x32_bf16 v[2:5], v[158:161], v[190:193], v[2:5]
	s_setprio 0
	s_add_i32 s18, 0, 0x18000
	s_add_i32 vcc_hi, 0, 0x1c000
	v_add_u32_e32 v142, s18, v245
	v_add_u32_e32 v158, vcc_hi, v245
	ds_read_b128 v[110:113], v142
	ds_read_b128 v[118:121], v142 offset:1024
	ds_read_b128 v[138:141], v142 offset:2048
	ds_read_b128 v[142:145], v142 offset:3072
	ds_read_b128 v[146:149], v158
	ds_read_b128 v[150:153], v158 offset:1024
	ds_read_b128 v[154:157], v158 offset:2048
	ds_read_b128 v[158:161], v158 offset:3072
	s_add_u32 s38, s46, s58
	s_addc_u32 s39, s47, 0
	s_mov_b32 m0, s94
	v_lshl_add_u64 v[222:223], s[38:39], 0, v[194:195]
	ds_read_b128 v[162:165], v247 offset:32768
	ds_read_b128 v[166:169], v247 offset:33792
	ds_read_b128 v[170:173], v247 offset:34816
	ds_read_b128 v[174:177], v247 offset:35840
	ds_read_b128 v[178:181], v247 offset:36864
	ds_read_b128 v[182:185], v247 offset:37888
	ds_read_b128 v[186:189], v247 offset:38912
	ds_read_b128 v[190:193], v247 offset:39936
	global_load_lds_dwordx4 v[222:223], off
	v_lshl_add_u64 v[222:223], s[38:39], 0, v[202:203]
	s_mov_b32 m0, s95
	s_nop 0
	global_load_lds_dwordx4 v[222:223], off
	s_waitcnt vmcnt(8)
	s_waitcnt lgkmcnt(0)
	s_barrier
	s_setprio 1
	s_waitcnt lgkmcnt(0)
	v_mfma_f32_16x16x32_bf16 v[130:133], v[110:113], v[162:165], v[130:133]
	v_mfma_f32_16x16x32_bf16 v[134:137], v[138:141], v[162:165], v[134:137]
	v_mfma_f32_16x16x32_bf16 v[114:117], v[110:113], v[170:173], v[114:117]
	v_mfma_f32_16x16x32_bf16 v[106:109], v[138:141], v[170:173], v[106:109]
	v_mfma_f32_16x16x32_bf16 v[94:97], v[110:113], v[178:181], v[94:97]
	v_mfma_f32_16x16x32_bf16 v[90:93], v[138:141], v[178:181], v[90:93]
	v_mfma_f32_16x16x32_bf16 v[78:81], v[110:113], v[186:189], v[78:81]
	v_mfma_f32_16x16x32_bf16 v[74:77], v[138:141], v[186:189], v[74:77]
	v_mfma_f32_16x16x32_bf16 v[130:133], v[118:121], v[166:169], v[130:133]
	v_mfma_f32_16x16x32_bf16 v[134:137], v[142:145], v[166:169], v[134:137]
	v_mfma_f32_16x16x32_bf16 v[114:117], v[118:121], v[174:177], v[114:117]
	v_mfma_f32_16x16x32_bf16 v[106:109], v[142:145], v[174:177], v[106:109]
	v_mfma_f32_16x16x32_bf16 v[94:97], v[118:121], v[182:185], v[94:97]
	v_mfma_f32_16x16x32_bf16 v[90:93], v[142:145], v[182:185], v[90:93]
	v_mfma_f32_16x16x32_bf16 v[78:81], v[118:121], v[190:193], v[78:81]
	v_mfma_f32_16x16x32_bf16 v[74:77], v[142:145], v[190:193], v[74:77]
	s_setprio 0
	s_setprio 1
	v_mfma_f32_16x16x32_bf16 v[126:129], v[146:149], v[162:165], v[126:129]
	v_mfma_f32_16x16x32_bf16 v[122:125], v[154:157], v[162:165], v[122:125]
	v_mfma_f32_16x16x32_bf16 v[102:105], v[146:149], v[170:173], v[102:105]
	v_mfma_f32_16x16x32_bf16 v[98:101], v[154:157], v[170:173], v[98:101]
	v_mfma_f32_16x16x32_bf16 v[86:89], v[146:149], v[178:181], v[86:89]
	v_mfma_f32_16x16x32_bf16 v[82:85], v[154:157], v[178:181], v[82:85]
	v_mfma_f32_16x16x32_bf16 v[70:73], v[146:149], v[186:189], v[70:73]
	v_mfma_f32_16x16x32_bf16 v[66:69], v[154:157], v[186:189], v[66:69]
	v_mfma_f32_16x16x32_bf16 v[126:129], v[150:153], v[166:169], v[126:129]
	v_mfma_f32_16x16x32_bf16 v[122:125], v[158:161], v[166:169], v[122:125]
	v_mfma_f32_16x16x32_bf16 v[102:105], v[150:153], v[174:177], v[102:105]
	v_mfma_f32_16x16x32_bf16 v[98:101], v[158:161], v[174:177], v[98:101]
	s_barrier
; #define PG8_STAGE(bufoff, gbase, voff) do { _Pragma("unroll") for (int _i = 0; _i < 2; ++_i) \
;         __builtin_amdgcn_global_load_lds((const unsigned*)((const char*)(gbase) + (voff)[_i]), (PG8_LAS unsigned*)(lds + (bufoff) + ldsw + _i * 8192), 16, 0, 0); } while (0)
; #define PG8_LDA(dst, b, h) do { _Pragma("unroll") for (int m = 0; m < 4; ++m) _Pragma("unroll") for (int k = 0; k < 2; ++k) dst[m][k] = *(const PG8_LAS bf16x8*)(lds + PG8_SA(b, h) + aoff + m * 2048 + k * 1024); } while (0)
; #define PG8_MMA(ai, bj, At, Bt) do { __builtin_amdgcn_s_setprio(1); _Pragma("unroll") for (int m = 0; m < 4; ++m) _Pragma("unroll") for (int n = 0; n < 2; ++n) _Pragma("unroll") for (int k = 0; k < 2; ++k) \
;         acc[ai][bj][m][n] = __builtin_amdgcn_mfma_f32_16x16x32_bf16(Bt[n][k], At[m][k], acc[ai][bj][m][n], 0, 0, 0); __builtin_amdgcn_s_setprio(0); } while (0)
; #define PG8_WAIT_V(n) asm volatile("s_waitcnt vmcnt(" #n ")" ::: "memory")
; #define PG8_WAIT_L(n) asm volatile("s_waitcnt lgkmcnt(" #n ")" ::: "memory")
; #define PG8_BAR __builtin_amdgcn_s_barrier()
; #define PG8_SCHED __builtin_amdgcn_sched_barrier(0)
; template <class Epi, class Sched, bool ALIGN_EPI = false, bool SP2 = false>
; __device__ __forceinline__ void gemm_phase(PG8_LAS unsigned char* lds, const Gemm g, const Sched& S, const Epi& E) {
;     ...
;             PG8_WAIT_V(8); PG8_WAIT_L(0); PG8_BAR; PG8_MMA(0, 0, At, B0); PG8_MMA(0, 1, At, B1); PG8_BAR; PG8_SCHED;
;             PG8_LDA(At, 1, 1); PG8_STAGE(PG8_SB(1, 0), b3, voffB); PG8_STAGE(PG8_SB(1, 1), b3 + hstep, voffB); PG8_STAGE(PG8_SA(1, 0), a3, voffA);
;             PG8_WAIT_V(8); PG8_WAIT_L(0); PG8_BAR; PG8_MMA(1, 0, At, B0); PG8_MMA(1, 1, At, B1); PG8_BAR; PG8_SCHED;
	v_mfma_f32_16x16x32_bf16 v[86:89], v[150:153], v[182:185], v[86:89]
	v_mfma_f32_16x16x32_bf16 v[82:85], v[158:161], v[182:185], v[82:85]
	v_mfma_f32_16x16x32_bf16 v[70:73], v[150:153], v[190:193], v[70:73]
	v_mfma_f32_16x16x32_bf16 v[66:69], v[158:161], v[190:193], v[66:69]
	s_setprio 0
	s_add_i32 s18, s18, s6
	v_lshl_add_u64 v[210:211], v[210:211], 0, s[30:31]
	s_mov_b32 m0, s18
	ds_read_b128 v[162:165], v247 offset:49152
	ds_read_b128 v[166:169], v247 offset:50176
	ds_read_b128 v[170:173], v247 offset:51200
	ds_read_b128 v[174:177], v247 offset:52224
	ds_read_b128 v[178:181], v247 offset:53248
	ds_read_b128 v[182:185], v247 offset:54272
	ds_read_b128 v[186:189], v247 offset:55296
	ds_read_b128 v[190:193], v247 offset:56320
	global_load_lds_dwordx4 v[210:211], off
	v_lshl_add_u64 v[210:211], v[212:213], 0, s[30:31]
	s_add_i32 m0, s18, 0x2000
	s_add_i32 s18, vcc_hi, s6
	global_load_lds_dwordx4 v[210:211], off
	v_lshl_add_u64 v[210:211], v[214:215], 0, s[30:31]
	s_mov_b32 m0, s18
	s_nop 0
	global_load_lds_dwordx4 v[210:211], off
	v_lshl_add_u64 v[210:211], v[216:217], 0, s[30:31]
	s_add_i32 m0, s18, 0x2000
	s_nop 0
	global_load_lds_dwordx4 v[210:211], off
	v_lshl_add_u64 v[210:211], v[218:219], 0, s[30:31]
	s_mov_b32 m0, s97
	s_nop 0
	global_load_lds_dwordx4 v[210:211], off
	v_lshl_add_u64 v[210:211], v[220:221], 0, s[30:31]
	s_mov_b32 m0, s98
	s_nop 0
	global_load_lds_dwordx4 v[210:211], off
	s_waitcnt vmcnt(8)
	s_waitcnt lgkmcnt(0)
	s_barrier
	s_setprio 1
	s_waitcnt lgkmcnt(0)
	v_mfma_f32_16x16x32_bf16 v[62:65], v[110:113], v[162:165], v[62:65]
	v_mfma_f32_16x16x32_bf16 v[58:61], v[138:141], v[162:165], v[58:61]
	v_mfma_f32_16x16x32_bf16 v[46:49], v[110:113], v[170:173], v[46:49]
	v_mfma_f32_16x16x32_bf16 v[42:45], v[138:141], v[170:173], v[42:45]
	v_mfma_f32_16x16x32_bf16 v[30:33], v[110:113], v[178:181], v[30:33]
	v_mfma_f32_16x16x32_bf16 v[26:29], v[138:141], v[178:181], v[26:29]
	v_mfma_f32_16x16x32_bf16 v[14:17], v[110:113], v[186:189], v[14:17]
	v_mfma_f32_16x16x32_bf16 v[10:13], v[138:141], v[186:189], v[10:13]
	v_mfma_f32_16x16x32_bf16 v[62:65], v[118:121], v[166:169], v[62:65]
	v_mfma_f32_16x16x32_bf16 v[58:61], v[142:145], v[166:169], v[58:61]
	v_mfma_f32_16x16x32_bf16 v[46:49], v[118:121], v[174:177], v[46:49]
	v_mfma_f32_16x16x32_bf16 v[42:45], v[142:145], v[174:177], v[42:45]
	v_mfma_f32_16x16x32_bf16 v[30:33], v[118:121], v[182:185], v[30:33]
	v_mfma_f32_16x16x32_bf16 v[26:29], v[142:145], v[182:185], v[26:29]
	v_mfma_f32_16x16x32_bf16 v[14:17], v[118:121], v[190:193], v[14:17]
	v_mfma_f32_16x16x32_bf16 v[10:13], v[142:145], v[190:193], v[10:13]
	s_setprio 0
	s_setprio 1
	v_mfma_f32_16x16x32_bf16 v[54:57], v[146:149], v[162:165], v[54:57]
	v_mfma_f32_16x16x32_bf16 v[50:53], v[154:157], v[162:165], v[50:53]
	v_mfma_f32_16x16x32_bf16 v[38:41], v[146:149], v[170:173], v[38:41]
	v_mfma_f32_16x16x32_bf16 v[34:37], v[154:157], v[170:173], v[34:37]
	v_mfma_f32_16x16x32_bf16 v[22:25], v[146:149], v[178:181], v[22:25]
	v_mfma_f32_16x16x32_bf16 v[18:21], v[154:157], v[178:181], v[18:21]
	v_mfma_f32_16x16x32_bf16 v[6:9], v[146:149], v[186:189], v[6:9]
	v_mfma_f32_16x16x32_bf16 v[2:5], v[154:157], v[186:189], v[2:5]
	v_mfma_f32_16x16x32_bf16 v[54:57], v[150:153], v[166:169], v[54:57]
	v_mfma_f32_16x16x32_bf16 v[50:53], v[158:161], v[166:169], v[50:53]
	v_mfma_f32_16x16x32_bf16 v[38:41], v[150:153], v[174:177], v[38:41]
	v_mfma_f32_16x16x32_bf16 v[34:37], v[158:161], v[174:177], v[34:37]
	s_barrier
	v_mfma_f32_16x16x32_bf16 v[22:25], v[150:153], v[182:185], v[22:25]
	v_mfma_f32_16x16x32_bf16 v[18:21], v[158:161], v[182:185], v[18:21]
	v_mfma_f32_16x16x32_bf16 v[6:9], v[150:153], v[190:193], v[6:9]
	v_mfma_f32_16x16x32_bf16 v[2:5], v[158:161], v[190:193], v[2:5]
	s_setprio 0
	s_add_u32 s48, s48, 0x100
	s_addc_u32 s49, s49, 0
	s_add_u32 s50, s50, 0x100
	s_addc_u32 s51, s51, 0
	s_cmp_ge_u32 vcc_lo, s96
	s_mov_b32 s46, vcc_lo
	s_cbranch_scc0 .LBB0_274
	s_and_b64 vcc, exec, s[72:73]
	s_cbranch_vccz .LBB0_277
	s_barrier

; #define PG8_STAGE(bufoff, gbase, voff) do { _Pragma("unroll") for (int _i = 0; _i < 2; ++_i) \
;         __builtin_amdgcn_global_load_lds((const unsigned*)((const char*)(gbase) + (voff)[_i]), (PG8_LAS unsigned*)(lds + (bufoff) + ldsw + _i * 8192), 16, 0, 0); } while (0)
; #define PG8_LDA(dst, b, h) do { _Pragma("unroll") for (int m = 0; m < 4; ++m) _Pragma("unroll") for (int k = 0; k < 2; ++k) dst[m][k] = *(const PG8_LAS bf16x8*)(lds + PG8_SA(b, h) + aoff + m * 2048 + k * 1024); } while (0)
; #define PG8_LDB(dst, b, h) do { _Pragma("unroll") for (int n = 0; n < 2; ++n) _Pragma("unroll") for (int k = 0; k < 2; ++k) dst[n][k] = *(const PG8_LAS bf16x8*)(lds + PG8_SB(b, h) + boff + n * 2048 + k * 1024); } while (0)
; #define PG8_MMA(ai, bj, At, Bt) do { __builtin_amdgcn_s_setprio(1); _Pragma("unroll") for (int m = 0; m < 4; ++m) _Pragma("unroll") for (int n = 0; n < 2; ++n) _Pragma("unroll") for (int k = 0; k < 2; ++k) \
;         acc[ai][bj][m][n] = __builtin_amdgcn_mfma_f32_16x16x32_bf16(Bt[n][k], At[m][k], acc[ai][bj][m][n], 0, 0, 0); __builtin_amdgcn_s_setprio(0); } while (0)
; #define PG8_WAIT_V(n) asm volatile("s_waitcnt vmcnt(" #n ")" ::: "memory")
; #define PG8_WAIT_L(n) asm volatile("s_waitcnt lgkmcnt(" #n ")" ::: "memory")
; #define PG8_BAR __builtin_amdgcn_s_barrier()
; #define PG8_SCHED __builtin_amdgcn_sched_barrier(0)
; template <class Epi, class Sched, bool ALIGN_EPI = false, bool SP2 = false>
; __device__ __forceinline__ void gemm_phase(PG8_LAS unsigned char* lds, const Gemm g, const Sched& S, const Epi& E) {
;     ...
;         for (int t = 0; t < nt; t += 2) {
;             const bool last = (t == nt - 2);
;             const char* a1 = cA + (size_t)(t + 1) * kstep;
;             const char* a2 = last ? nA : cA + (size_t)(t + 2) * kstep; const char* b2 = last ? nB : cB + (size_t)(t + 2) * kstep;
;             const char* a3 = a2 + kstep; const char* b3 = b2 + kstep;
;             if (last && has_next) S.a_ready(nxt);
;             if constexpr (SP2) {
;             PG8_LDB(B0, 0, 0); PG8_LDB(B1, 0, 1); PG8_SCHED; PG8_LDA(At, 0, 0); PG8_STAGE(PG8_SA(1, 1), a1 + hstep, voffA);
;             PG8_WAIT_V(8); PG8_WAIT_L(0); PG8_BAR; PG8_MMA(0, 0, At, B0); PG8_MMA(0, 1, At, B1); PG8_BAR; PG8_SCHED;
;             PG8_LDA(At, 0, 1); PG8_STAGE(PG8_SB(0, 0), b2, voffB); PG8_STAGE(PG8_SB(0, 1), b2 + hstep, voffB); PG8_STAGE(PG8_SA(0, 0), a2, voffA);
.LBB0_408:
	s_add_u32 s38, s48, 0xfffc0080
	s_addc_u32 s39, s49, -1
	s_add_i32 s85, 0, 0x10000
	s_cmp_eq_u32 s84, 12
	s_cselect_b32 s73, s21, s39
	s_cselect_b32 s72, s27, s38
	v_add_u32_e32 v0, s85, v167
	s_cselect_b32 s47, s29, s69
	s_cselect_b32 s46, s33, s53
	s_add_i32 s38, 0, 0x14000
	ds_read_b128 v[142:145], v0
	ds_read_b128 v[146:149], v0 offset:1024
	ds_read_b128 v[150:153], v0 offset:2048
	ds_read_b128 v[154:157], v0 offset:3072
	v_add_u32_e32 v0, s38, v167
	ds_read_b128 v[158:161], v0
	ds_read_b128 v[162:165], v0 offset:1024
	ds_read_b128 v[172:175], v0 offset:2048
	ds_read_b128 v[176:179], v0 offset:3072
	v_lshl_add_u64 v[218:219], s[48:49], 0, v[138:139]
	s_add_i32 m0, s76, 0xc000
	ds_read_b128 v[180:183], v170
	ds_read_b128 v[184:187], v170 offset:1024
	ds_read_b128 v[188:191], v170 offset:2048
	ds_read_b128 v[192:195], v170 offset:3072
	ds_read_b128 v[202:205], v170 offset:4096
	ds_read_b128 v[206:209], v170 offset:5120
	ds_read_b128 v[210:213], v170 offset:6144
	ds_read_b128 v[214:217], v170 offset:7168
	global_load_lds_dwordx4 v[218:219], off
	v_lshl_add_u64 v[218:219], s[48:49], 0, v[140:141]
	s_add_i32 m0, s76, 0xe000
	s_nop 0
	global_load_lds_dwordx4 v[218:219], off
	s_waitcnt vmcnt(8)
	s_waitcnt lgkmcnt(0)
	s_barrier
	s_setprio 1
	s_waitcnt lgkmcnt(0)
	v_mfma_f32_16x16x32_bf16 v[122:125], v[142:145], v[180:183], v[122:125]
	v_mfma_f32_16x16x32_bf16 v[126:129], v[150:153], v[180:183], v[126:129]
	v_mfma_f32_16x16x32_bf16 v[106:109], v[142:145], v[188:191], v[106:109]
	v_mfma_f32_16x16x32_bf16 v[110:113], v[150:153], v[188:191], v[110:113]
	v_mfma_f32_16x16x32_bf16 v[90:93], v[142:145], v[202:205], v[90:93]
	v_mfma_f32_16x16x32_bf16 v[94:97], v[150:153], v[202:205], v[94:97]
	v_mfma_f32_16x16x32_bf16 v[74:77], v[142:145], v[210:213], v[74:77]
	v_mfma_f32_16x16x32_bf16 v[78:81], v[150:153], v[210:213], v[78:81]
	v_mfma_f32_16x16x32_bf16 v[122:125], v[146:149], v[184:187], v[122:125]
	v_mfma_f32_16x16x32_bf16 v[126:129], v[154:157], v[184:187], v[126:129]
	v_mfma_f32_16x16x32_bf16 v[106:109], v[146:149], v[192:195], v[106:109]
	v_mfma_f32_16x16x32_bf16 v[110:113], v[154:157], v[192:195], v[110:113]
	v_mfma_f32_16x16x32_bf16 v[90:93], v[146:149], v[206:209], v[90:93]
	v_mfma_f32_16x16x32_bf16 v[94:97], v[154:157], v[206:209], v[94:97]
	v_mfma_f32_16x16x32_bf16 v[74:77], v[146:149], v[214:217], v[74:77]
	v_mfma_f32_16x16x32_bf16 v[78:81], v[154:157], v[214:217], v[78:81]
	s_setprio 0
	s_setprio 1
	v_mfma_f32_16x16x32_bf16 v[114:117], v[158:161], v[180:183], v[114:117]
	v_mfma_f32_16x16x32_bf16 v[118:121], v[172:175], v[180:183], v[118:121]
	v_mfma_f32_16x16x32_bf16 v[98:101], v[158:161], v[188:191], v[98:101]
	v_mfma_f32_16x16x32_bf16 v[102:105], v[172:175], v[188:191], v[102:105]
	v_mfma_f32_16x16x32_bf16 v[82:85], v[158:161], v[202:205], v[82:85]
	v_mfma_f32_16x16x32_bf16 v[86:89], v[172:175], v[202:205], v[86:89]
	v_mfma_f32_16x16x32_bf16 v[66:69], v[158:161], v[210:213], v[66:69]
	v_mfma_f32_16x16x32_bf16 v[70:73], v[172:175], v[210:213], v[70:73]
	v_mfma_f32_16x16x32_bf16 v[114:117], v[162:165], v[184:187], v[114:117]
	v_mfma_f32_16x16x32_bf16 v[118:121], v[176:179], v[184:187], v[118:121]
	v_mfma_f32_16x16x32_bf16 v[98:101], v[162:165], v[192:195], v[98:101]
	v_mfma_f32_16x16x32_bf16 v[102:105], v[176:179], v[192:195], v[102:105]
	s_barrier
	v_mfma_f32_16x16x32_bf16 v[82:85], v[162:165], v[206:209], v[82:85]
	v_mfma_f32_16x16x32_bf16 v[86:89], v[176:179], v[206:209], v[86:89]
	v_mfma_f32_16x16x32_bf16 v[66:69], v[162:165], v[214:217], v[66:69]
	v_mfma_f32_16x16x32_bf16 v[70:73], v[176:179], v[214:217], v[70:73]
	s_setprio 0
	s_add_i32 s39, s85, s75
	v_lshl_add_u64 v[218:219], s[46:47], 0, v[134:135]
	s_mov_b32 m0, s39
	ds_read_b128 v[180:183], v170 offset:16384
	ds_read_b128 v[184:187], v170 offset:17408
	ds_read_b128 v[188:191], v170 offset:18432
	ds_read_b128 v[192:195], v170 offset:19456
	ds_read_b128 v[202:205], v170 offset:20480
	ds_read_b128 v[206:209], v170 offset:21504
	ds_read_b128 v[210:213], v170 offset:22528
	ds_read_b128 v[214:217], v170 offset:23552
	global_load_lds_dwordx4 v[218:219], off
	s_add_i32 m0, s39, 0x2000
	s_add_u32 s92, s46, 0x40000
	v_lshl_add_u64 v[220:221], s[46:47], 0, v[130:131]
	s_addc_u32 s93, s47, 0
	s_add_i32 s38, s38, s75
	global_load_lds_dwordx4 v[220:221], off
	v_lshl_add_u64 v[222:223], s[92:93], 0, v[134:135]
	s_mov_b32 m0, s38
	v_lshl_add_u64 v[224:225], s[72:73], 0, v[132:133]
	global_load_lds_dwordx4 v[222:223], off
	v_lshl_add_u64 v[222:223], s[92:93], 0, v[130:131]
	s_add_i32 m0, s38, 0x2000
	s_nop 0
	global_load_lds_dwordx4 v[222:223], off
	v_lshl_add_u64 v[222:223], s[72:73], 0, v[136:137]
	s_mov_b32 m0, s76
	s_nop 0
	global_load_lds_dwordx4 v[222:223], off
	s_mov_b32 m0, s77
	s_nop 0
	global_load_lds_dwordx4 v[224:225], off
	s_waitcnt vmcnt(8)
	s_waitcnt lgkmcnt(0)
	s_barrier
; #define PG8_STAGE(bufoff, gbase, voff) do { _Pragma("unroll") for (int _i = 0; _i < 2; ++_i) \
;         __builtin_amdgcn_global_load_lds((const unsigned*)((const char*)(gbase) + (voff)[_i]), (PG8_LAS unsigned*)(lds + (bufoff) + ldsw + _i * 8192), 16, 0, 0); } while (0)
; #define PG8_LDA(dst, b, h) do { _Pragma("unroll") for (int m = 0; m < 4; ++m) _Pragma("unroll") for (int k = 0; k < 2; ++k) dst[m][k] = *(const PG8_LAS bf16x8*)(lds + PG8_SA(b, h) + aoff + m * 2048 + k * 1024); } while (0)
; #define PG8_LDB(dst, b, h) do { _Pragma("unroll") for (int n = 0; n < 2; ++n) _Pragma("unroll") for (int k = 0; k < 2; ++k) dst[n][k] = *(const PG8_LAS bf16x8*)(lds + PG8_SB(b, h) + boff + n * 2048 + k * 1024); } while (0)
; #define PG8_MMA(ai, bj, At, Bt) do { __builtin_amdgcn_s_setprio(1); _Pragma("unroll") for (int m = 0; m < 4; ++m) _Pragma("unroll") for (int n = 0; n < 2; ++n) _Pragma("unroll") for (int k = 0; k < 2; ++k) \
;         acc[ai][bj][m][n] = __builtin_amdgcn_mfma_f32_16x16x32_bf16(Bt[n][k], At[m][k], acc[ai][bj][m][n], 0, 0, 0); __builtin_amdgcn_s_setprio(0); } while (0)
; #define PG8_WAIT_V(n) asm volatile("s_waitcnt vmcnt(" #n ")" ::: "memory")
; #define PG8_WAIT_L(n) asm volatile("s_waitcnt lgkmcnt(" #n ")" ::: "memory")
; #define PG8_BAR __builtin_amdgcn_s_barrier()
; #define PG8_SCHED __builtin_amdgcn_sched_barrier(0)
; template <class Epi, class Sched, bool ALIGN_EPI = false, bool SP2 = false>
; __device__ __forceinline__ void gemm_phase(PG8_LAS unsigned char* lds, const Gemm g, const Sched& S, const Epi& E) {
;     ...
;             PG8_WAIT_V(8); PG8_WAIT_L(0); PG8_BAR; PG8_MMA(1, 0, At, B0); PG8_MMA(1, 1, At, B1); PG8_BAR; PG8_SCHED;
;             PG8_LDB(B0, 1, 0); PG8_LDB(B1, 1, 1); PG8_SCHED; PG8_LDA(At, 1, 0); PG8_STAGE(PG8_SA(0, 1), a2 + hstep, voffA);
;             PG8_WAIT_V(8); PG8_WAIT_L(0); PG8_BAR; PG8_MMA(0, 0, At, B0); PG8_MMA(0, 1, At, B1); PG8_BAR; PG8_SCHED;
	s_setprio 1
	s_waitcnt lgkmcnt(0)
	v_mfma_f32_16x16x32_bf16 v[58:61], v[142:145], v[180:183], v[58:61]
	v_mfma_f32_16x16x32_bf16 v[62:65], v[150:153], v[180:183], v[62:65]
	v_mfma_f32_16x16x32_bf16 v[42:45], v[142:145], v[188:191], v[42:45]
	v_mfma_f32_16x16x32_bf16 v[46:49], v[150:153], v[188:191], v[46:49]
	v_mfma_f32_16x16x32_bf16 v[26:29], v[142:145], v[202:205], v[26:29]
	v_mfma_f32_16x16x32_bf16 v[30:33], v[150:153], v[202:205], v[30:33]
	v_mfma_f32_16x16x32_bf16 v[10:13], v[142:145], v[210:213], v[10:13]
	v_mfma_f32_16x16x32_bf16 v[14:17], v[150:153], v[210:213], v[14:17]
	v_mfma_f32_16x16x32_bf16 v[58:61], v[146:149], v[184:187], v[58:61]
	v_mfma_f32_16x16x32_bf16 v[62:65], v[154:157], v[184:187], v[62:65]
	v_mfma_f32_16x16x32_bf16 v[42:45], v[146:149], v[192:195], v[42:45]
	v_mfma_f32_16x16x32_bf16 v[46:49], v[154:157], v[192:195], v[46:49]
	v_mfma_f32_16x16x32_bf16 v[26:29], v[146:149], v[206:209], v[26:29]
	v_mfma_f32_16x16x32_bf16 v[30:33], v[154:157], v[206:209], v[30:33]
	v_mfma_f32_16x16x32_bf16 v[10:13], v[146:149], v[214:217], v[10:13]
	v_mfma_f32_16x16x32_bf16 v[14:17], v[154:157], v[214:217], v[14:17]
	s_setprio 0
	s_setprio 1
	v_mfma_f32_16x16x32_bf16 v[50:53], v[158:161], v[180:183], v[50:53]
	v_mfma_f32_16x16x32_bf16 v[54:57], v[172:175], v[180:183], v[54:57]
	v_mfma_f32_16x16x32_bf16 v[34:37], v[158:161], v[188:191], v[34:37]
	v_mfma_f32_16x16x32_bf16 v[38:41], v[172:175], v[188:191], v[38:41]
	v_mfma_f32_16x16x32_bf16 v[18:21], v[158:161], v[202:205], v[18:21]
	v_mfma_f32_16x16x32_bf16 v[22:25], v[172:175], v[202:205], v[22:25]
	v_mfma_f32_16x16x32_bf16 v[2:5], v[158:161], v[210:213], v[2:5]
	v_mfma_f32_16x16x32_bf16 v[6:9], v[172:175], v[210:213], v[6:9]
	v_mfma_f32_16x16x32_bf16 v[50:53], v[162:165], v[184:187], v[50:53]
	v_mfma_f32_16x16x32_bf16 v[54:57], v[176:179], v[184:187], v[54:57]
	v_mfma_f32_16x16x32_bf16 v[34:37], v[162:165], v[192:195], v[34:37]
	v_mfma_f32_16x16x32_bf16 v[38:41], v[176:179], v[192:195], v[38:41]
	s_barrier
	v_mfma_f32_16x16x32_bf16 v[18:21], v[162:165], v[206:209], v[18:21]
	v_mfma_f32_16x16x32_bf16 v[22:25], v[176:179], v[206:209], v[22:25]
	v_mfma_f32_16x16x32_bf16 v[2:5], v[162:165], v[214:217], v[2:5]
	v_mfma_f32_16x16x32_bf16 v[6:9], v[176:179], v[214:217], v[6:9]
	s_setprio 0
	s_add_i32 s38, 0, 0x18000
	v_add_u32_e32 v0, s38, v167
	s_add_i32 s39, 0, 0x1c000
	ds_read_b128 v[142:145], v0
	ds_read_b128 v[146:149], v0 offset:1024
	ds_read_b128 v[150:153], v0 offset:2048
	ds_read_b128 v[154:157], v0 offset:3072
	v_add_u32_e32 v0, s39, v167
	ds_read_b128 v[158:161], v0
	ds_read_b128 v[162:165], v0 offset:1024
	ds_read_b128 v[172:175], v0 offset:2048
	ds_read_b128 v[176:179], v0 offset:3072
	s_add_u32 s72, s72, 0x40000
	s_addc_u32 s73, s73, 0
	s_mov_b32 m0, s78
	v_lshl_add_u64 v[226:227], s[72:73], 0, v[136:137]
	ds_read_b128 v[180:183], v170 offset:32768
	ds_read_b128 v[184:187], v170 offset:33792
	ds_read_b128 v[188:191], v170 offset:34816
	ds_read_b128 v[192:195], v170 offset:35840
	ds_read_b128 v[202:205], v170 offset:36864
	ds_read_b128 v[206:209], v170 offset:37888
	ds_read_b128 v[210:213], v170 offset:38912
	ds_read_b128 v[214:217], v170 offset:39936
	global_load_lds_dwordx4 v[226:227], off
	v_lshl_add_u64 v[226:227], s[72:73], 0, v[132:133]
	s_mov_b32 m0, s79
	s_nop 0
	global_load_lds_dwordx4 v[226:227], off
	s_waitcnt vmcnt(8)
	s_waitcnt lgkmcnt(0)
	s_barrier
	s_setprio 1
	s_waitcnt lgkmcnt(0)
	v_mfma_f32_16x16x32_bf16 v[122:125], v[142:145], v[180:183], v[122:125]
	v_mfma_f32_16x16x32_bf16 v[126:129], v[150:153], v[180:183], v[126:129]
	v_mfma_f32_16x16x32_bf16 v[106:109], v[142:145], v[188:191], v[106:109]
	v_mfma_f32_16x16x32_bf16 v[110:113], v[150:153], v[188:191], v[110:113]
	v_mfma_f32_16x16x32_bf16 v[90:93], v[142:145], v[202:205], v[90:93]
	v_mfma_f32_16x16x32_bf16 v[94:97], v[150:153], v[202:205], v[94:97]
	v_mfma_f32_16x16x32_bf16 v[74:77], v[142:145], v[210:213], v[74:77]
	v_mfma_f32_16x16x32_bf16 v[78:81], v[150:153], v[210:213], v[78:81]
	v_mfma_f32_16x16x32_bf16 v[122:125], v[146:149], v[184:187], v[122:125]
	v_mfma_f32_16x16x32_bf16 v[126:129], v[154:157], v[184:187], v[126:129]
	v_mfma_f32_16x16x32_bf16 v[106:109], v[146:149], v[192:195], v[106:109]
	v_mfma_f32_16x16x32_bf16 v[110:113], v[154:157], v[192:195], v[110:113]
	v_mfma_f32_16x16x32_bf16 v[90:93], v[146:149], v[206:209], v[90:93]
	v_mfma_f32_16x16x32_bf16 v[94:97], v[154:157], v[206:209], v[94:97]
	v_mfma_f32_16x16x32_bf16 v[74:77], v[146:149], v[214:217], v[74:77]
	v_mfma_f32_16x16x32_bf16 v[78:81], v[154:157], v[214:217], v[78:81]
	s_setprio 0
	s_setprio 1
	v_mfma_f32_16x16x32_bf16 v[114:117], v[158:161], v[180:183], v[114:117]
	v_mfma_f32_16x16x32_bf16 v[118:121], v[172:175], v[180:183], v[118:121]
	v_mfma_f32_16x16x32_bf16 v[98:101], v[158:161], v[188:191], v[98:101]
	v_mfma_f32_16x16x32_bf16 v[102:105], v[172:175], v[188:191], v[102:105]
	v_mfma_f32_16x16x32_bf16 v[82:85], v[158:161], v[202:205], v[82:85]
	v_mfma_f32_16x16x32_bf16 v[86:89], v[172:175], v[202:205], v[86:89]
	v_mfma_f32_16x16x32_bf16 v[66:69], v[158:161], v[210:213], v[66:69]
	v_mfma_f32_16x16x32_bf16 v[70:73], v[172:175], v[210:213], v[70:73]
	v_mfma_f32_16x16x32_bf16 v[114:117], v[162:165], v[184:187], v[114:117]
	v_mfma_f32_16x16x32_bf16 v[118:121], v[176:179], v[184:187], v[118:121]
	v_mfma_f32_16x16x32_bf16 v[98:101], v[162:165], v[192:195], v[98:101]
	v_mfma_f32_16x16x32_bf16 v[102:105], v[176:179], v[192:195], v[102:105]
	s_barrier
; #define PG8_STAGE(bufoff, gbase, voff) do { _Pragma("unroll") for (int _i = 0; _i < 2; ++_i) \
;         __builtin_amdgcn_global_load_lds((const unsigned*)((const char*)(gbase) + (voff)[_i]), (PG8_LAS unsigned*)(lds + (bufoff) + ldsw + _i * 8192), 16, 0, 0); } while (0)
; #define PG8_LDA(dst, b, h) do { _Pragma("unroll") for (int m = 0; m < 4; ++m) _Pragma("unroll") for (int k = 0; k < 2; ++k) dst[m][k] = *(const PG8_LAS bf16x8*)(lds + PG8_SA(b, h) + aoff + m * 2048 + k * 1024); } while (0)
; #define PG8_MMA(ai, bj, At, Bt) do { __builtin_amdgcn_s_setprio(1); _Pragma("unroll") for (int m = 0; m < 4; ++m) _Pragma("unroll") for (int n = 0; n < 2; ++n) _Pragma("unroll") for (int k = 0; k < 2; ++k) \
;         acc[ai][bj][m][n] = __builtin_amdgcn_mfma_f32_16x16x32_bf16(Bt[n][k], At[m][k], acc[ai][bj][m][n], 0, 0, 0); __builtin_amdgcn_s_setprio(0); } while (0)
; #define PG8_WAIT_V(n) asm volatile("s_waitcnt vmcnt(" #n ")" ::: "memory")
; #define PG8_WAIT_L(n) asm volatile("s_waitcnt lgkmcnt(" #n ")" ::: "memory")
; #define PG8_BAR __builtin_amdgcn_s_barrier()
; #define PG8_SCHED __builtin_amdgcn_sched_barrier(0)
; template <class Epi, class Sched, bool ALIGN_EPI = false, bool SP2 = false>
; __device__ __forceinline__ void gemm_phase(PG8_LAS unsigned char* lds, const Gemm g, const Sched& S, const Epi& E) {
;     ...
;             PG8_WAIT_V(8); PG8_WAIT_L(0); PG8_BAR; PG8_MMA(0, 0, At, B0); PG8_MMA(0, 1, At, B1); PG8_BAR; PG8_SCHED;
;             PG8_LDA(At, 1, 1); PG8_STAGE(PG8_SB(1, 0), b3, voffB); PG8_STAGE(PG8_SB(1, 1), b3 + hstep, voffB); PG8_STAGE(PG8_SA(1, 0), a3, voffA);
;             PG8_WAIT_V(8); PG8_WAIT_L(0); PG8_BAR; PG8_MMA(1, 0, At, B0); PG8_MMA(1, 1, At, B1); PG8_BAR; PG8_SCHED;
	v_mfma_f32_16x16x32_bf16 v[82:85], v[162:165], v[206:209], v[82:85]
	v_mfma_f32_16x16x32_bf16 v[86:89], v[176:179], v[206:209], v[86:89]
	v_mfma_f32_16x16x32_bf16 v[66:69], v[162:165], v[214:217], v[66:69]
	v_mfma_f32_16x16x32_bf16 v[70:73], v[176:179], v[214:217], v[70:73]
	s_setprio 0
	s_add_i32 s38, s38, s75
	v_lshl_add_u64 v[218:219], v[218:219], 0, s[30:31]
	s_mov_b32 m0, s38
	ds_read_b128 v[180:183], v170 offset:49152
	ds_read_b128 v[184:187], v170 offset:50176
	ds_read_b128 v[188:191], v170 offset:51200
	ds_read_b128 v[192:195], v170 offset:52224
	ds_read_b128 v[202:205], v170 offset:53248
	ds_read_b128 v[206:209], v170 offset:54272
	ds_read_b128 v[210:213], v170 offset:55296
	ds_read_b128 v[214:217], v170 offset:56320
	global_load_lds_dwordx4 v[218:219], off
	s_add_i32 m0, s38, 0x2000
	s_add_u32 s46, s46, 0x40080
	v_lshl_add_u64 v[218:219], v[220:221], 0, s[30:31]
	s_addc_u32 s47, s47, 0
	s_add_i32 s38, s39, s75
	global_load_lds_dwordx4 v[218:219], off
	v_lshl_add_u64 v[218:219], s[46:47], 0, v[134:135]
	s_mov_b32 m0, s38
	s_nop 0
	global_load_lds_dwordx4 v[218:219], off
	v_lshl_add_u64 v[218:219], s[46:47], 0, v[130:131]
	s_add_i32 m0, s38, 0x2000
	s_nop 0
	global_load_lds_dwordx4 v[218:219], off
	v_lshl_add_u64 v[218:219], v[222:223], 0, s[30:31]
	s_mov_b32 m0, s80
	s_nop 0
	global_load_lds_dwordx4 v[218:219], off
	v_lshl_add_u64 v[218:219], v[224:225], 0, s[30:31]
	s_mov_b32 m0, s81
	s_nop 0
	global_load_lds_dwordx4 v[218:219], off
	s_waitcnt vmcnt(8)
	s_waitcnt lgkmcnt(0)
	s_barrier
	s_setprio 1
	s_waitcnt lgkmcnt(0)
	v_mfma_f32_16x16x32_bf16 v[58:61], v[142:145], v[180:183], v[58:61]
	v_mfma_f32_16x16x32_bf16 v[62:65], v[150:153], v[180:183], v[62:65]
	v_mfma_f32_16x16x32_bf16 v[42:45], v[142:145], v[188:191], v[42:45]
	v_mfma_f32_16x16x32_bf16 v[46:49], v[150:153], v[188:191], v[46:49]
	v_mfma_f32_16x16x32_bf16 v[26:29], v[142:145], v[202:205], v[26:29]
	v_mfma_f32_16x16x32_bf16 v[30:33], v[150:153], v[202:205], v[30:33]
	v_mfma_f32_16x16x32_bf16 v[10:13], v[142:145], v[210:213], v[10:13]
	v_mfma_f32_16x16x32_bf16 v[14:17], v[150:153], v[210:213], v[14:17]
	v_mfma_f32_16x16x32_bf16 v[58:61], v[146:149], v[184:187], v[58:61]
	v_mfma_f32_16x16x32_bf16 v[62:65], v[154:157], v[184:187], v[62:65]
	v_mfma_f32_16x16x32_bf16 v[42:45], v[146:149], v[192:195], v[42:45]
	v_mfma_f32_16x16x32_bf16 v[46:49], v[154:157], v[192:195], v[46:49]
	v_mfma_f32_16x16x32_bf16 v[26:29], v[146:149], v[206:209], v[26:29]
	v_mfma_f32_16x16x32_bf16 v[30:33], v[154:157], v[206:209], v[30:33]
	v_mfma_f32_16x16x32_bf16 v[10:13], v[146:149], v[214:217], v[10:13]
	v_mfma_f32_16x16x32_bf16 v[14:17], v[154:157], v[214:217], v[14:17]
	s_setprio 0
	s_setprio 1
	v_mfma_f32_16x16x32_bf16 v[50:53], v[158:161], v[180:183], v[50:53]
	v_mfma_f32_16x16x32_bf16 v[54:57], v[172:175], v[180:183], v[54:57]
	v_mfma_f32_16x16x32_bf16 v[34:37], v[158:161], v[188:191], v[34:37]
	v_mfma_f32_16x16x32_bf16 v[38:41], v[172:175], v[188:191], v[38:41]
	v_mfma_f32_16x16x32_bf16 v[18:21], v[158:161], v[202:205], v[18:21]
	v_mfma_f32_16x16x32_bf16 v[22:25], v[172:175], v[202:205], v[22:25]
	v_mfma_f32_16x16x32_bf16 v[2:5], v[158:161], v[210:213], v[2:5]
	v_mfma_f32_16x16x32_bf16 v[6:9], v[172:175], v[210:213], v[6:9]
	v_mfma_f32_16x16x32_bf16 v[50:53], v[162:165], v[184:187], v[50:53]
	v_mfma_f32_16x16x32_bf16 v[54:57], v[176:179], v[184:187], v[54:57]
	v_mfma_f32_16x16x32_bf16 v[34:37], v[162:165], v[192:195], v[34:37]
	v_mfma_f32_16x16x32_bf16 v[38:41], v[176:179], v[192:195], v[38:41]
	s_barrier
	v_mfma_f32_16x16x32_bf16 v[18:21], v[162:165], v[206:209], v[18:21]
	v_mfma_f32_16x16x32_bf16 v[22:25], v[176:179], v[206:209], v[22:25]
	v_mfma_f32_16x16x32_bf16 v[2:5], v[162:165], v[214:217], v[2:5]
	v_mfma_f32_16x16x32_bf16 v[6:9], v[176:179], v[214:217], v[6:9]
	s_setprio 0
	s_add_i32 s84, s84, 2
	s_add_u32 s48, s48, 0x100
	s_addc_u32 s49, s49, 0
	s_add_u32 s53, s53, 0x100
	s_addc_u32 s69, s69, 0
	s_cmp_gt_u32 s84, 13
	s_cbranch_scc0 .LBB0_408
	s_and_b64 vcc, exec, s[64:65]
	s_cbranch_vccz .LBB0_411
	s_barrier
